# GEMM MFMA order over the 32-MFMA segment: accumulator pairs chained, B fragment (srcA) kept stationary for 8 MFMAs, snake over A fragments
# baseline (speedup 1.0000x reference)
.LBB0_101:
	ds_read_b128 v[154:157], v151
	ds_read_b128 v[158:161], v151 offset:1024
	ds_read_b128 v[162:165], v151 offset:2048
	ds_read_b128 v[166:169], v151 offset:3072
	ds_read_b128 v[170:173], v152
	ds_read_b128 v[174:177], v152 offset:1024
	ds_read_b128 v[188:191], v152 offset:2048
	ds_read_b128 v[192:195], v152 offset:3072
	s_add_u32 s40, s36, s38
	s_addc_u32 s41, s37, s39
	s_add_u32 s44, s40, 0x100
	s_addc_u32 s45, s41, 0
	s_add_u32 s42, s66, s38
	s_addc_u32 s43, s67, s39
	s_add_u32 s40, s40, 0x180
	s_addc_u32 s41, s41, 0
	s_cmpk_eq_i32 s38, 0x1f00
	s_cselect_b32 s41, s65, s41
	s_cselect_b32 s40, s64, s40
	s_cselect_b32 s43, s35, s43
	s_cselect_b32 s42, s34, s42
	s_cselect_b32 s45, s23, s45
	s_cselect_b32 s44, s22, s44
	s_mov_b32 m0, s57
	v_lshl_add_u64 v[178:179], v[146:147], 0, s[38:39]
	ds_read_b128 v[196:199], v153
	ds_read_b128 v[200:203], v153 offset:1024
	ds_read_b128 v[204:207], v153 offset:2048
	ds_read_b128 v[208:211], v153 offset:3072
	ds_read_b128 v[214:217], v153 offset:4096
	ds_read_b128 v[218:221], v153 offset:5120
	ds_read_b128 v[222:225], v153 offset:6144
	ds_read_b128 v[226:229], v153 offset:7168
	global_load_lds_dwordx4 v[178:179], off
	v_lshl_add_u64 v[178:179], v[148:149], 0, s[38:39]
	s_add_i32 m0, s47, 0xe000
	s_nop 0
	global_load_lds_dwordx4 v[178:179], off
	s_waitcnt vmcnt(8)
	s_waitcnt lgkmcnt(0)
	s_barrier
	s_waitcnt lgkmcnt(0)
	v_mfma_f32_16x16x32_bf16 v[126:129], v[154:157], v[196:199], v[126:129]
	v_mfma_f32_16x16x32_bf16 v[126:129], v[158:161], v[200:203], v[126:129]
	v_mfma_f32_16x16x32_bf16 v[118:121], v[158:161], v[208:211], v[118:121]
	v_mfma_f32_16x16x32_bf16 v[118:121], v[154:157], v[204:207], v[118:121]
	v_mfma_f32_16x16x32_bf16 v[102:105], v[154:157], v[214:217], v[102:105]
	v_mfma_f32_16x16x32_bf16 v[102:105], v[158:161], v[218:221], v[102:105]
	v_mfma_f32_16x16x32_bf16 v[86:89], v[158:161], v[226:229], v[86:89]
	v_mfma_f32_16x16x32_bf16 v[86:89], v[154:157], v[222:225], v[86:89]
	v_mfma_f32_16x16x32_bf16 v[78:81], v[162:165], v[222:225], v[78:81]
	v_mfma_f32_16x16x32_bf16 v[78:81], v[166:169], v[226:229], v[78:81]
	v_mfma_f32_16x16x32_bf16 v[94:97], v[166:169], v[218:221], v[94:97]
	v_mfma_f32_16x16x32_bf16 v[94:97], v[162:165], v[214:217], v[94:97]
	v_mfma_f32_16x16x32_bf16 v[110:113], v[162:165], v[204:207], v[110:113]
	v_mfma_f32_16x16x32_bf16 v[110:113], v[166:169], v[208:211], v[110:113]
	v_mfma_f32_16x16x32_bf16 v[122:125], v[166:169], v[200:203], v[122:125]
	v_mfma_f32_16x16x32_bf16 v[122:125], v[162:165], v[196:199], v[122:125]
	v_mfma_f32_16x16x32_bf16 v[114:117], v[170:173], v[196:199], v[114:117]
	v_mfma_f32_16x16x32_bf16 v[114:117], v[174:177], v[200:203], v[114:117]
	v_mfma_f32_16x16x32_bf16 v[98:101], v[174:177], v[208:211], v[98:101]
	v_mfma_f32_16x16x32_bf16 v[98:101], v[170:173], v[204:207], v[98:101]
	v_mfma_f32_16x16x32_bf16 v[82:85], v[170:173], v[214:217], v[82:85]
	v_mfma_f32_16x16x32_bf16 v[82:85], v[174:177], v[218:221], v[82:85]
	v_mfma_f32_16x16x32_bf16 v[70:73], v[174:177], v[226:229], v[70:73]
	v_mfma_f32_16x16x32_bf16 v[70:73], v[170:173], v[222:225], v[70:73]
	v_mfma_f32_16x16x32_bf16 v[66:69], v[188:191], v[222:225], v[66:69]
	v_mfma_f32_16x16x32_bf16 v[66:69], v[192:195], v[226:229], v[66:69]
	v_mfma_f32_16x16x32_bf16 v[74:77], v[192:195], v[218:221], v[74:77]
	v_mfma_f32_16x16x32_bf16 v[74:77], v[188:191], v[214:217], v[74:77]
	v_mfma_f32_16x16x32_bf16 v[90:93], v[188:191], v[204:207], v[90:93]
	v_mfma_f32_16x16x32_bf16 v[90:93], v[192:195], v[208:211], v[90:93]
	v_mfma_f32_16x16x32_bf16 v[106:109], v[192:195], v[200:203], v[106:109]
	v_mfma_f32_16x16x32_bf16 v[106:109], v[188:191], v[196:199], v[106:109]
	s_barrier
	s_add_i32 s69, s54, s3
	s_mov_b32 m0, s69
	ds_read_b128 v[196:199], v153 offset:16384
	ds_read_b128 v[200:203], v153 offset:17408
	ds_read_b128 v[204:207], v153 offset:18432
	ds_read_b128 v[208:211], v153 offset:19456
	ds_read_b128 v[214:217], v153 offset:20480
	ds_read_b128 v[218:221], v153 offset:21504
	ds_read_b128 v[222:225], v153 offset:22528
	ds_read_b128 v[226:229], v153 offset:23552
	global_load_lds_dwordx4 v136, s[42:43]
	s_add_i32 m0, s69, 0x2000
	s_add_u32 s70, s42, 0x108000
	s_addc_u32 s71, s43, 0
	s_add_i32 s69, s55, s3
	global_load_lds_dwordx4 v140, s[42:43]
	s_mov_b32 m0, s69
	s_nop 0
	global_load_lds_dwordx4 v136, s[70:71]
	s_add_i32 m0, s69, 0x2000
	s_nop 0
	global_load_lds_dwordx4 v140, s[70:71]
	s_mov_b32 m0, s47
	s_nop 0
	global_load_lds_dwordx4 v134, s[44:45]
	s_mov_b32 m0, s48
	s_nop 0
	global_load_lds_dwordx4 v138, s[44:45]
	s_waitcnt vmcnt(8)
	s_waitcnt lgkmcnt(0)
	s_barrier
	s_waitcnt lgkmcnt(0)
	v_mfma_f32_16x16x32_bf16 v[62:65], v[154:157], v[196:199], v[62:65]
	v_mfma_f32_16x16x32_bf16 v[62:65], v[158:161], v[200:203], v[62:65]
	v_mfma_f32_16x16x32_bf16 v[54:57], v[158:161], v[208:211], v[54:57]
	v_mfma_f32_16x16x32_bf16 v[54:57], v[154:157], v[204:207], v[54:57]
	v_mfma_f32_16x16x32_bf16 v[38:41], v[154:157], v[214:217], v[38:41]
	v_mfma_f32_16x16x32_bf16 v[38:41], v[158:161], v[218:221], v[38:41]
	v_mfma_f32_16x16x32_bf16 v[22:25], v[158:161], v[226:229], v[22:25]
	v_mfma_f32_16x16x32_bf16 v[22:25], v[154:157], v[222:225], v[22:25]
	v_mfma_f32_16x16x32_bf16 v[14:17], v[162:165], v[222:225], v[14:17]
	v_mfma_f32_16x16x32_bf16 v[14:17], v[166:169], v[226:229], v[14:17]
	v_mfma_f32_16x16x32_bf16 v[30:33], v[166:169], v[218:221], v[30:33]
	v_mfma_f32_16x16x32_bf16 v[30:33], v[162:165], v[214:217], v[30:33]
	v_mfma_f32_16x16x32_bf16 v[46:49], v[162:165], v[204:207], v[46:49]
	v_mfma_f32_16x16x32_bf16 v[46:49], v[166:169], v[208:211], v[46:49]
	v_mfma_f32_16x16x32_bf16 v[58:61], v[166:169], v[200:203], v[58:61]
	v_mfma_f32_16x16x32_bf16 v[58:61], v[162:165], v[196:199], v[58:61]
	v_mfma_f32_16x16x32_bf16 v[50:53], v[170:173], v[196:199], v[50:53]
	v_mfma_f32_16x16x32_bf16 v[50:53], v[174:177], v[200:203], v[50:53]
	v_mfma_f32_16x16x32_bf16 v[34:37], v[174:177], v[208:211], v[34:37]
	v_mfma_f32_16x16x32_bf16 v[34:37], v[170:173], v[204:207], v[34:37]
	v_mfma_f32_16x16x32_bf16 v[18:21], v[170:173], v[214:217], v[18:21]
	v_mfma_f32_16x16x32_bf16 v[18:21], v[174:177], v[218:221], v[18:21]
	v_mfma_f32_16x16x32_bf16 v[6:9], v[174:177], v[226:229], v[6:9]
	v_mfma_f32_16x16x32_bf16 v[6:9], v[170:173], v[222:225], v[6:9]
	v_mfma_f32_16x16x32_bf16 v[2:5], v[188:191], v[222:225], v[2:5]
	v_mfma_f32_16x16x32_bf16 v[2:5], v[192:195], v[226:229], v[2:5]
	v_mfma_f32_16x16x32_bf16 v[10:13], v[192:195], v[218:221], v[10:13]
	v_mfma_f32_16x16x32_bf16 v[10:13], v[188:191], v[214:217], v[10:13]
	v_mfma_f32_16x16x32_bf16 v[26:29], v[188:191], v[204:207], v[26:29]
	v_mfma_f32_16x16x32_bf16 v[26:29], v[192:195], v[208:211], v[26:29]
	v_mfma_f32_16x16x32_bf16 v[42:45], v[192:195], v[200:203], v[42:45]
	v_mfma_f32_16x16x32_bf16 v[42:45], v[188:191], v[196:199], v[42:45]
	s_barrier
	s_add_i32 s69, 0, 0x18000
	s_add_i32 s70, 0, 0x1c000
	v_add_u32_e32 v166, s69, v133
	v_add_u32_e32 v187, s70, v133
	ds_read_b128 v[154:157], v166
	ds_read_b128 v[158:161], v166 offset:1024
	ds_read_b128 v[162:165], v166 offset:2048
	ds_read_b128 v[166:169], v166 offset:3072
	ds_read_b128 v[170:173], v187
	ds_read_b128 v[174:177], v187 offset:1024
	ds_read_b128 v[188:191], v187 offset:2048
	ds_read_b128 v[192:195], v187 offset:3072
	s_add_u32 s44, s44, 0x108000
	s_addc_u32 s45, s45, 0
	s_mov_b32 m0, s49
	ds_read_b128 v[196:199], v153 offset:32768
	ds_read_b128 v[200:203], v153 offset:33792
	ds_read_b128 v[204:207], v153 offset:34816
	ds_read_b128 v[208:211], v153 offset:35840
	ds_read_b128 v[214:217], v153 offset:36864
	ds_read_b128 v[218:221], v153 offset:37888
	ds_read_b128 v[222:225], v153 offset:38912
	ds_read_b128 v[226:229], v153 offset:39936
	global_load_lds_dwordx4 v134, s[44:45]
	s_mov_b32 m0, s50
	s_nop 0
	global_load_lds_dwordx4 v138, s[44:45]
	s_waitcnt vmcnt(8)
	s_waitcnt lgkmcnt(0)
	s_barrier
	s_waitcnt lgkmcnt(0)
	v_mfma_f32_16x16x32_bf16 v[126:129], v[154:157], v[196:199], v[126:129]
	v_mfma_f32_16x16x32_bf16 v[126:129], v[158:161], v[200:203], v[126:129]
	v_mfma_f32_16x16x32_bf16 v[118:121], v[158:161], v[208:211], v[118:121]
	v_mfma_f32_16x16x32_bf16 v[118:121], v[154:157], v[204:207], v[118:121]
	v_mfma_f32_16x16x32_bf16 v[102:105], v[154:157], v[214:217], v[102:105]
	v_mfma_f32_16x16x32_bf16 v[102:105], v[158:161], v[218:221], v[102:105]
	v_mfma_f32_16x16x32_bf16 v[86:89], v[158:161], v[226:229], v[86:89]
	v_mfma_f32_16x16x32_bf16 v[86:89], v[154:157], v[222:225], v[86:89]
	v_mfma_f32_16x16x32_bf16 v[78:81], v[162:165], v[222:225], v[78:81]
	v_mfma_f32_16x16x32_bf16 v[78:81], v[166:169], v[226:229], v[78:81]
	v_mfma_f32_16x16x32_bf16 v[94:97], v[166:169], v[218:221], v[94:97]
	v_mfma_f32_16x16x32_bf16 v[94:97], v[162:165], v[214:217], v[94:97]
	v_mfma_f32_16x16x32_bf16 v[110:113], v[162:165], v[204:207], v[110:113]
	v_mfma_f32_16x16x32_bf16 v[110:113], v[166:169], v[208:211], v[110:113]
	v_mfma_f32_16x16x32_bf16 v[122:125], v[166:169], v[200:203], v[122:125]
	v_mfma_f32_16x16x32_bf16 v[122:125], v[162:165], v[196:199], v[122:125]
	v_mfma_f32_16x16x32_bf16 v[114:117], v[170:173], v[196:199], v[114:117]
	v_mfma_f32_16x16x32_bf16 v[114:117], v[174:177], v[200:203], v[114:117]
	v_mfma_f32_16x16x32_bf16 v[98:101], v[174:177], v[208:211], v[98:101]
	v_mfma_f32_16x16x32_bf16 v[98:101], v[170:173], v[204:207], v[98:101]
	v_mfma_f32_16x16x32_bf16 v[82:85], v[170:173], v[214:217], v[82:85]
	v_mfma_f32_16x16x32_bf16 v[82:85], v[174:177], v[218:221], v[82:85]
	v_mfma_f32_16x16x32_bf16 v[70:73], v[174:177], v[226:229], v[70:73]
	v_mfma_f32_16x16x32_bf16 v[70:73], v[170:173], v[222:225], v[70:73]
	v_mfma_f32_16x16x32_bf16 v[66:69], v[188:191], v[222:225], v[66:69]
	v_mfma_f32_16x16x32_bf16 v[66:69], v[192:195], v[226:229], v[66:69]
	v_mfma_f32_16x16x32_bf16 v[74:77], v[192:195], v[218:221], v[74:77]
	v_mfma_f32_16x16x32_bf16 v[74:77], v[188:191], v[214:217], v[74:77]
	v_mfma_f32_16x16x32_bf16 v[90:93], v[188:191], v[204:207], v[90:93]
	v_mfma_f32_16x16x32_bf16 v[90:93], v[192:195], v[208:211], v[90:93]
	v_mfma_f32_16x16x32_bf16 v[106:109], v[192:195], v[200:203], v[106:109]
	v_mfma_f32_16x16x32_bf16 v[106:109], v[188:191], v[196:199], v[106:109]
	s_barrier
	s_add_i32 s44, s69, s3
	s_add_u32 s42, s42, 0x80
	s_addc_u32 s43, s43, 0
	s_mov_b32 m0, s44
	ds_read_b128 v[196:199], v153 offset:49152
	ds_read_b128 v[200:203], v153 offset:50176
	ds_read_b128 v[204:207], v153 offset:51200
	ds_read_b128 v[208:211], v153 offset:52224
	ds_read_b128 v[214:217], v153 offset:53248
	ds_read_b128 v[218:221], v153 offset:54272
	ds_read_b128 v[222:225], v153 offset:55296
	ds_read_b128 v[226:229], v153 offset:56320
	global_load_lds_dwordx4 v136, s[42:43]
	s_add_i32 m0, s44, 0x2000
	s_add_i32 s44, s70, s3
	global_load_lds_dwordx4 v140, s[42:43]
	s_add_u32 s42, s42, 0x108000
	s_addc_u32 s43, s43, 0
	s_mov_b32 m0, s44
	s_nop 0
	global_load_lds_dwordx4 v136, s[42:43]
	s_add_i32 m0, s44, 0x2000
	s_nop 0
	global_load_lds_dwordx4 v140, s[42:43]
	s_mov_b32 m0, s52
	s_nop 0
	global_load_lds_dwordx4 v134, s[40:41]
	s_mov_b32 m0, s53
	s_nop 0
	global_load_lds_dwordx4 v138, s[40:41]
	s_waitcnt vmcnt(8)
	s_waitcnt lgkmcnt(0)
	s_barrier
	s_waitcnt lgkmcnt(0)
	v_mfma_f32_16x16x32_bf16 v[62:65], v[154:157], v[196:199], v[62:65]
	v_mfma_f32_16x16x32_bf16 v[62:65], v[158:161], v[200:203], v[62:65]
	v_mfma_f32_16x16x32_bf16 v[54:57], v[158:161], v[208:211], v[54:57]
	v_mfma_f32_16x16x32_bf16 v[54:57], v[154:157], v[204:207], v[54:57]
	v_mfma_f32_16x16x32_bf16 v[38:41], v[154:157], v[214:217], v[38:41]
	v_mfma_f32_16x16x32_bf16 v[38:41], v[158:161], v[218:221], v[38:41]
	v_mfma_f32_16x16x32_bf16 v[22:25], v[158:161], v[226:229], v[22:25]
	v_mfma_f32_16x16x32_bf16 v[22:25], v[154:157], v[222:225], v[22:25]
	v_mfma_f32_16x16x32_bf16 v[14:17], v[162:165], v[222:225], v[14:17]
	v_mfma_f32_16x16x32_bf16 v[14:17], v[166:169], v[226:229], v[14:17]
	v_mfma_f32_16x16x32_bf16 v[30:33], v[166:169], v[218:221], v[30:33]
	v_mfma_f32_16x16x32_bf16 v[30:33], v[162:165], v[214:217], v[30:33]
	v_mfma_f32_16x16x32_bf16 v[46:49], v[162:165], v[204:207], v[46:49]
	v_mfma_f32_16x16x32_bf16 v[46:49], v[166:169], v[208:211], v[46:49]
	v_mfma_f32_16x16x32_bf16 v[58:61], v[166:169], v[200:203], v[58:61]
	v_mfma_f32_16x16x32_bf16 v[58:61], v[162:165], v[196:199], v[58:61]
	v_mfma_f32_16x16x32_bf16 v[50:53], v[170:173], v[196:199], v[50:53]
	v_mfma_f32_16x16x32_bf16 v[50:53], v[174:177], v[200:203], v[50:53]
	v_mfma_f32_16x16x32_bf16 v[34:37], v[174:177], v[208:211], v[34:37]
	v_mfma_f32_16x16x32_bf16 v[34:37], v[170:173], v[204:207], v[34:37]
	v_mfma_f32_16x16x32_bf16 v[18:21], v[170:173], v[214:217], v[18:21]
	v_mfma_f32_16x16x32_bf16 v[18:21], v[174:177], v[218:221], v[18:21]
	v_mfma_f32_16x16x32_bf16 v[6:9], v[174:177], v[226:229], v[6:9]
	v_mfma_f32_16x16x32_bf16 v[6:9], v[170:173], v[222:225], v[6:9]
	v_mfma_f32_16x16x32_bf16 v[2:5], v[188:191], v[222:225], v[2:5]
	v_mfma_f32_16x16x32_bf16 v[2:5], v[192:195], v[226:229], v[2:5]
	v_mfma_f32_16x16x32_bf16 v[10:13], v[192:195], v[218:221], v[10:13]
	v_mfma_f32_16x16x32_bf16 v[10:13], v[188:191], v[214:217], v[10:13]
	v_mfma_f32_16x16x32_bf16 v[26:29], v[188:191], v[204:207], v[26:29]
	v_mfma_f32_16x16x32_bf16 v[26:29], v[192:195], v[208:211], v[26:29]
	v_mfma_f32_16x16x32_bf16 v[42:45], v[192:195], v[200:203], v[42:45]
	v_mfma_f32_16x16x32_bf16 v[42:45], v[188:191], v[196:199], v[42:45]
	s_barrier
	s_add_i32 s68, s68, 2
	s_add_u32 s38, s38, 0x100
	s_addc_u32 s39, s39, 0
	s_cmp_gt_u32 s68, 61
	s_cbranch_scc0 .LBB0_101
	s_and_b64 vcc, exec, s[20:21]
	s_cbranch_vccz .LBB0_104
	s_barrier

.LBB0_235:
	ds_read_b128 v[156:159], v150
	ds_read_b128 v[160:163], v150 offset:1024
	ds_read_b128 v[164:167], v150 offset:2048
	ds_read_b128 v[168:171], v150 offset:3072
	ds_read_b128 v[172:175], v151
	ds_read_b128 v[176:179], v151 offset:1024
	ds_read_b128 v[180:183], v151 offset:2048
	ds_read_b128 v[184:187], v151 offset:3072
	s_add_u32 s36, s4, s34
	s_addc_u32 s37, s5, s35
	s_add_u32 s40, s36, 0x100
	s_addc_u32 s41, s37, 0
	s_add_u32 s38, s62, s34
	s_addc_u32 s39, s63, s35
	s_add_u32 s36, s36, 0x180
	s_addc_u32 s37, s37, 0
	s_cmpk_eq_i32 s34, 0x1f00
	s_cselect_b32 s37, s61, s37
	s_cselect_b32 s36, s60, s36
	s_cselect_b32 s39, s31, s39
	s_cselect_b32 s38, s30, s38
	s_cselect_b32 s41, s23, s41
	s_cselect_b32 s40, s22, s40
	s_mov_b32 m0, s46
	v_lshl_add_u64 v[222:223], v[146:147], 0, s[34:35]
	ds_read_b128 v[188:191], v152
	ds_read_b128 v[192:195], v152 offset:1024
	ds_read_b128 v[196:199], v152 offset:2048
	ds_read_b128 v[200:203], v152 offset:3072
	ds_read_b128 v[204:207], v152 offset:4096
	ds_read_b128 v[208:211], v152 offset:5120
	ds_read_b128 v[214:217], v152 offset:6144
	ds_read_b128 v[218:221], v152 offset:7168
	global_load_lds_dwordx4 v[222:223], off
	v_lshl_add_u64 v[222:223], v[148:149], 0, s[34:35]
	s_mov_b32 m0, s47
	s_nop 0
	global_load_lds_dwordx4 v[222:223], off
	s_waitcnt vmcnt(8)
	s_waitcnt lgkmcnt(0)
	s_barrier
	s_waitcnt lgkmcnt(0)
	v_mfma_f32_16x16x32_bf16 v[126:129], v[156:159], v[188:191], v[126:129]
	v_mfma_f32_16x16x32_bf16 v[126:129], v[160:163], v[192:195], v[126:129]
	v_mfma_f32_16x16x32_bf16 v[110:113], v[160:163], v[200:203], v[110:113]
	v_mfma_f32_16x16x32_bf16 v[110:113], v[156:159], v[196:199], v[110:113]
	v_mfma_f32_16x16x32_bf16 v[94:97], v[156:159], v[204:207], v[94:97]
	v_mfma_f32_16x16x32_bf16 v[94:97], v[160:163], v[208:211], v[94:97]
	v_mfma_f32_16x16x32_bf16 v[78:81], v[160:163], v[218:221], v[78:81]
	v_mfma_f32_16x16x32_bf16 v[78:81], v[156:159], v[214:217], v[78:81]
	v_mfma_f32_16x16x32_bf16 v[74:77], v[164:167], v[214:217], v[74:77]
	v_mfma_f32_16x16x32_bf16 v[74:77], v[168:171], v[218:221], v[74:77]
	v_mfma_f32_16x16x32_bf16 v[90:93], v[168:171], v[208:211], v[90:93]
	v_mfma_f32_16x16x32_bf16 v[90:93], v[164:167], v[204:207], v[90:93]
	v_mfma_f32_16x16x32_bf16 v[106:109], v[164:167], v[196:199], v[106:109]
	v_mfma_f32_16x16x32_bf16 v[106:109], v[168:171], v[200:203], v[106:109]
	v_mfma_f32_16x16x32_bf16 v[122:125], v[168:171], v[192:195], v[122:125]
	v_mfma_f32_16x16x32_bf16 v[122:125], v[164:167], v[188:191], v[122:125]
	v_mfma_f32_16x16x32_bf16 v[118:121], v[172:175], v[188:191], v[118:121]
	v_mfma_f32_16x16x32_bf16 v[118:121], v[176:179], v[192:195], v[118:121]
	v_mfma_f32_16x16x32_bf16 v[102:105], v[176:179], v[200:203], v[102:105]
	v_mfma_f32_16x16x32_bf16 v[102:105], v[172:175], v[196:199], v[102:105]
	v_mfma_f32_16x16x32_bf16 v[86:89], v[172:175], v[204:207], v[86:89]
	v_mfma_f32_16x16x32_bf16 v[86:89], v[176:179], v[208:211], v[86:89]
	v_mfma_f32_16x16x32_bf16 v[70:73], v[176:179], v[218:221], v[70:73]
	v_mfma_f32_16x16x32_bf16 v[70:73], v[172:175], v[214:217], v[70:73]
	v_mfma_f32_16x16x32_bf16 v[66:69], v[180:183], v[214:217], v[66:69]
	v_mfma_f32_16x16x32_bf16 v[66:69], v[184:187], v[218:221], v[66:69]
	v_mfma_f32_16x16x32_bf16 v[82:85], v[184:187], v[208:211], v[82:85]
	v_mfma_f32_16x16x32_bf16 v[82:85], v[180:183], v[204:207], v[82:85]
	v_mfma_f32_16x16x32_bf16 v[98:101], v[180:183], v[196:199], v[98:101]
	v_mfma_f32_16x16x32_bf16 v[98:101], v[184:187], v[200:203], v[98:101]
	v_mfma_f32_16x16x32_bf16 v[114:117], v[184:187], v[192:195], v[114:117]
	v_mfma_f32_16x16x32_bf16 v[114:117], v[180:183], v[188:191], v[114:117]
	s_barrier
	s_mov_b32 m0, s48
	s_add_u32 s66, s38, 0x108000
	ds_read_b128 v[188:191], v152 offset:16384
	ds_read_b128 v[192:195], v152 offset:17408
	ds_read_b128 v[196:199], v152 offset:18432
	ds_read_b128 v[200:203], v152 offset:19456
	ds_read_b128 v[204:207], v152 offset:20480
	ds_read_b128 v[208:211], v152 offset:21504
	ds_read_b128 v[214:217], v152 offset:22528
	ds_read_b128 v[218:221], v152 offset:23552
	global_load_lds_dwordx4 v132, s[38:39]
	s_mov_b32 m0, s49
	s_addc_u32 s67, s39, 0
	global_load_lds_dwordx4 v136, s[38:39]
	s_mov_b32 m0, s50
	s_nop 0
	global_load_lds_dwordx4 v132, s[66:67]
	s_mov_b32 m0, s51
	s_nop 0
	global_load_lds_dwordx4 v136, s[66:67]
	s_mov_b32 m0, s3
	s_nop 0
	global_load_lds_dwordx4 v130, s[40:41]
	s_mov_b32 m0, s33
	s_nop 0
	global_load_lds_dwordx4 v134, s[40:41]
	s_waitcnt vmcnt(8)
	s_waitcnt lgkmcnt(0)
	s_barrier
	s_waitcnt lgkmcnt(0)
	v_mfma_f32_16x16x32_bf16 v[62:65], v[156:159], v[188:191], v[62:65]
	v_mfma_f32_16x16x32_bf16 v[62:65], v[160:163], v[192:195], v[62:65]
	v_mfma_f32_16x16x32_bf16 v[46:49], v[160:163], v[200:203], v[46:49]
	v_mfma_f32_16x16x32_bf16 v[46:49], v[156:159], v[196:199], v[46:49]
	v_mfma_f32_16x16x32_bf16 v[30:33], v[156:159], v[204:207], v[30:33]
	v_mfma_f32_16x16x32_bf16 v[30:33], v[160:163], v[208:211], v[30:33]
	v_mfma_f32_16x16x32_bf16 v[14:17], v[160:163], v[218:221], v[14:17]
	v_mfma_f32_16x16x32_bf16 v[14:17], v[156:159], v[214:217], v[14:17]
	v_mfma_f32_16x16x32_bf16 v[10:13], v[164:167], v[214:217], v[10:13]
	v_mfma_f32_16x16x32_bf16 v[10:13], v[168:171], v[218:221], v[10:13]
	v_mfma_f32_16x16x32_bf16 v[26:29], v[168:171], v[208:211], v[26:29]
	v_mfma_f32_16x16x32_bf16 v[26:29], v[164:167], v[204:207], v[26:29]
	v_mfma_f32_16x16x32_bf16 v[42:45], v[164:167], v[196:199], v[42:45]
	v_mfma_f32_16x16x32_bf16 v[42:45], v[168:171], v[200:203], v[42:45]
	v_mfma_f32_16x16x32_bf16 v[58:61], v[168:171], v[192:195], v[58:61]
	v_mfma_f32_16x16x32_bf16 v[58:61], v[164:167], v[188:191], v[58:61]
	v_mfma_f32_16x16x32_bf16 v[54:57], v[172:175], v[188:191], v[54:57]
	v_mfma_f32_16x16x32_bf16 v[54:57], v[176:179], v[192:195], v[54:57]
	v_mfma_f32_16x16x32_bf16 v[38:41], v[176:179], v[200:203], v[38:41]
	v_mfma_f32_16x16x32_bf16 v[38:41], v[172:175], v[196:199], v[38:41]
	v_mfma_f32_16x16x32_bf16 v[22:25], v[172:175], v[204:207], v[22:25]
	v_mfma_f32_16x16x32_bf16 v[22:25], v[176:179], v[208:211], v[22:25]
	v_mfma_f32_16x16x32_bf16 v[6:9], v[176:179], v[218:221], v[6:9]
	v_mfma_f32_16x16x32_bf16 v[6:9], v[172:175], v[214:217], v[6:9]
	v_mfma_f32_16x16x32_bf16 v[2:5], v[180:183], v[214:217], v[2:5]
	v_mfma_f32_16x16x32_bf16 v[2:5], v[184:187], v[218:221], v[2:5]
	v_mfma_f32_16x16x32_bf16 v[18:21], v[184:187], v[208:211], v[18:21]
	v_mfma_f32_16x16x32_bf16 v[18:21], v[180:183], v[204:207], v[18:21]
	v_mfma_f32_16x16x32_bf16 v[34:37], v[180:183], v[196:199], v[34:37]
	v_mfma_f32_16x16x32_bf16 v[34:37], v[184:187], v[200:203], v[34:37]
	v_mfma_f32_16x16x32_bf16 v[50:53], v[184:187], v[192:195], v[50:53]
	v_mfma_f32_16x16x32_bf16 v[50:53], v[180:183], v[188:191], v[50:53]
	s_barrier
	ds_read_b128 v[156:159], v153
	ds_read_b128 v[160:163], v153 offset:1024
	ds_read_b128 v[164:167], v153 offset:2048
	ds_read_b128 v[168:171], v153 offset:3072
	ds_read_b128 v[172:175], v154
	ds_read_b128 v[176:179], v154 offset:1024
	ds_read_b128 v[180:183], v154 offset:2048
	ds_read_b128 v[184:187], v154 offset:3072
	s_add_u32 s40, s40, 0x108000
	s_addc_u32 s41, s41, 0
	s_mov_b32 m0, s42
	ds_read_b128 v[188:191], v152 offset:32768
	ds_read_b128 v[192:195], v152 offset:33792
	ds_read_b128 v[196:199], v152 offset:34816
	ds_read_b128 v[200:203], v152 offset:35840
	ds_read_b128 v[204:207], v152 offset:36864
	ds_read_b128 v[208:211], v152 offset:37888
	ds_read_b128 v[214:217], v152 offset:38912
	ds_read_b128 v[218:221], v152 offset:39936
	global_load_lds_dwordx4 v130, s[40:41]
	s_mov_b32 m0, s43
	s_nop 0
	global_load_lds_dwordx4 v134, s[40:41]
	s_waitcnt vmcnt(8)
	s_waitcnt lgkmcnt(0)
	s_barrier
	s_waitcnt lgkmcnt(0)
	v_mfma_f32_16x16x32_bf16 v[126:129], v[156:159], v[188:191], v[126:129]
	v_mfma_f32_16x16x32_bf16 v[126:129], v[160:163], v[192:195], v[126:129]
	v_mfma_f32_16x16x32_bf16 v[110:113], v[160:163], v[200:203], v[110:113]
	v_mfma_f32_16x16x32_bf16 v[110:113], v[156:159], v[196:199], v[110:113]
	v_mfma_f32_16x16x32_bf16 v[94:97], v[156:159], v[204:207], v[94:97]
	v_mfma_f32_16x16x32_bf16 v[94:97], v[160:163], v[208:211], v[94:97]
	v_mfma_f32_16x16x32_bf16 v[78:81], v[160:163], v[218:221], v[78:81]
	v_mfma_f32_16x16x32_bf16 v[78:81], v[156:159], v[214:217], v[78:81]
	v_mfma_f32_16x16x32_bf16 v[74:77], v[164:167], v[214:217], v[74:77]
	v_mfma_f32_16x16x32_bf16 v[74:77], v[168:171], v[218:221], v[74:77]
	v_mfma_f32_16x16x32_bf16 v[90:93], v[168:171], v[208:211], v[90:93]
	v_mfma_f32_16x16x32_bf16 v[90:93], v[164:167], v[204:207], v[90:93]
	v_mfma_f32_16x16x32_bf16 v[106:109], v[164:167], v[196:199], v[106:109]
	v_mfma_f32_16x16x32_bf16 v[106:109], v[168:171], v[200:203], v[106:109]
	v_mfma_f32_16x16x32_bf16 v[122:125], v[168:171], v[192:195], v[122:125]
	v_mfma_f32_16x16x32_bf16 v[122:125], v[164:167], v[188:191], v[122:125]
	v_mfma_f32_16x16x32_bf16 v[118:121], v[172:175], v[188:191], v[118:121]
	v_mfma_f32_16x16x32_bf16 v[118:121], v[176:179], v[192:195], v[118:121]
	v_mfma_f32_16x16x32_bf16 v[102:105], v[176:179], v[200:203], v[102:105]
	v_mfma_f32_16x16x32_bf16 v[102:105], v[172:175], v[196:199], v[102:105]
	v_mfma_f32_16x16x32_bf16 v[86:89], v[172:175], v[204:207], v[86:89]
	v_mfma_f32_16x16x32_bf16 v[86:89], v[176:179], v[208:211], v[86:89]
	v_mfma_f32_16x16x32_bf16 v[70:73], v[176:179], v[218:221], v[70:73]
	v_mfma_f32_16x16x32_bf16 v[70:73], v[172:175], v[214:217], v[70:73]
	v_mfma_f32_16x16x32_bf16 v[66:69], v[180:183], v[214:217], v[66:69]
	v_mfma_f32_16x16x32_bf16 v[66:69], v[184:187], v[218:221], v[66:69]
	v_mfma_f32_16x16x32_bf16 v[82:85], v[184:187], v[208:211], v[82:85]
	v_mfma_f32_16x16x32_bf16 v[82:85], v[180:183], v[204:207], v[82:85]
	v_mfma_f32_16x16x32_bf16 v[98:101], v[180:183], v[196:199], v[98:101]
	v_mfma_f32_16x16x32_bf16 v[98:101], v[184:187], v[200:203], v[98:101]
	v_mfma_f32_16x16x32_bf16 v[114:117], v[184:187], v[192:195], v[114:117]
	v_mfma_f32_16x16x32_bf16 v[114:117], v[180:183], v[188:191], v[114:117]
	s_barrier
	s_mov_b32 m0, s53
	s_add_u32 s38, s38, 0x80
	s_addc_u32 s39, s39, 0
	ds_read_b128 v[188:191], v152 offset:49152
	ds_read_b128 v[192:195], v152 offset:50176
	ds_read_b128 v[196:199], v152 offset:51200
	ds_read_b128 v[200:203], v152 offset:52224
	ds_read_b128 v[204:207], v152 offset:53248
	ds_read_b128 v[208:211], v152 offset:54272
	ds_read_b128 v[214:217], v152 offset:55296
	ds_read_b128 v[218:221], v152 offset:56320
	global_load_lds_dwordx4 v132, s[38:39]
	s_mov_b32 m0, s54
	s_add_i32 s40, s52, s2
	global_load_lds_dwordx4 v136, s[38:39]
	s_add_u32 s38, s38, 0x108000
	s_addc_u32 s39, s39, 0
	s_mov_b32 m0, s40
	s_nop 0
	global_load_lds_dwordx4 v132, s[38:39]
	s_add_i32 m0, s40, 0x2000
	s_nop 0
	global_load_lds_dwordx4 v136, s[38:39]
	s_mov_b32 m0, s44
	s_nop 0
	global_load_lds_dwordx4 v130, s[36:37]
	s_mov_b32 m0, s45
	s_nop 0
	global_load_lds_dwordx4 v134, s[36:37]
	s_waitcnt vmcnt(8)
	s_waitcnt lgkmcnt(0)
	s_barrier
	s_waitcnt lgkmcnt(0)
	v_mfma_f32_16x16x32_bf16 v[62:65], v[156:159], v[188:191], v[62:65]
	v_mfma_f32_16x16x32_bf16 v[62:65], v[160:163], v[192:195], v[62:65]
	v_mfma_f32_16x16x32_bf16 v[46:49], v[160:163], v[200:203], v[46:49]
	v_mfma_f32_16x16x32_bf16 v[46:49], v[156:159], v[196:199], v[46:49]
	v_mfma_f32_16x16x32_bf16 v[30:33], v[156:159], v[204:207], v[30:33]
	v_mfma_f32_16x16x32_bf16 v[30:33], v[160:163], v[208:211], v[30:33]
	v_mfma_f32_16x16x32_bf16 v[14:17], v[160:163], v[218:221], v[14:17]
	v_mfma_f32_16x16x32_bf16 v[14:17], v[156:159], v[214:217], v[14:17]
	v_mfma_f32_16x16x32_bf16 v[10:13], v[164:167], v[214:217], v[10:13]
	v_mfma_f32_16x16x32_bf16 v[10:13], v[168:171], v[218:221], v[10:13]
	v_mfma_f32_16x16x32_bf16 v[26:29], v[168:171], v[208:211], v[26:29]
	v_mfma_f32_16x16x32_bf16 v[26:29], v[164:167], v[204:207], v[26:29]
	v_mfma_f32_16x16x32_bf16 v[42:45], v[164:167], v[196:199], v[42:45]
	v_mfma_f32_16x16x32_bf16 v[42:45], v[168:171], v[200:203], v[42:45]
	v_mfma_f32_16x16x32_bf16 v[58:61], v[168:171], v[192:195], v[58:61]
	v_mfma_f32_16x16x32_bf16 v[58:61], v[164:167], v[188:191], v[58:61]
	v_mfma_f32_16x16x32_bf16 v[54:57], v[172:175], v[188:191], v[54:57]
	v_mfma_f32_16x16x32_bf16 v[54:57], v[176:179], v[192:195], v[54:57]
	v_mfma_f32_16x16x32_bf16 v[38:41], v[176:179], v[200:203], v[38:41]
	v_mfma_f32_16x16x32_bf16 v[38:41], v[172:175], v[196:199], v[38:41]
	v_mfma_f32_16x16x32_bf16 v[22:25], v[172:175], v[204:207], v[22:25]
	v_mfma_f32_16x16x32_bf16 v[22:25], v[176:179], v[208:211], v[22:25]
	v_mfma_f32_16x16x32_bf16 v[6:9], v[176:179], v[218:221], v[6:9]
	v_mfma_f32_16x16x32_bf16 v[6:9], v[172:175], v[214:217], v[6:9]
	v_mfma_f32_16x16x32_bf16 v[2:5], v[180:183], v[214:217], v[2:5]
	v_mfma_f32_16x16x32_bf16 v[2:5], v[184:187], v[218:221], v[2:5]
	v_mfma_f32_16x16x32_bf16 v[18:21], v[184:187], v[208:211], v[18:21]
	v_mfma_f32_16x16x32_bf16 v[18:21], v[180:183], v[204:207], v[18:21]
	v_mfma_f32_16x16x32_bf16 v[34:37], v[180:183], v[196:199], v[34:37]
	v_mfma_f32_16x16x32_bf16 v[34:37], v[184:187], v[200:203], v[34:37]
	v_mfma_f32_16x16x32_bf16 v[50:53], v[184:187], v[192:195], v[50:53]
	v_mfma_f32_16x16x32_bf16 v[50:53], v[180:183], v[188:191], v[50:53]
	s_barrier
	s_add_i32 s64, s64, 2
	s_add_u32 s34, s34, 0x100
	s_addc_u32 s35, s35, 0
	s_cmp_gt_u32 s64, 61
	s_cbranch_scc0 .LBB0_235
	s_and_b64 vcc, exec, s[20:21]
	s_cbranch_vccz .LBB0_238
	s_barrier

.LBB0_434:
	ds_read_b128 v[134:137], v204
	ds_read_b128 v[138:141], v204 offset:1024
	ds_read_b128 v[142:145], v204 offset:2048
	ds_read_b128 v[146:149], v204 offset:3072
	ds_read_b128 v[150:153], v205
	ds_read_b128 v[154:157], v205 offset:1024
	ds_read_b128 v[158:161], v205 offset:2048
	ds_read_b128 v[162:165], v205 offset:3072
	s_add_u32 s34, s22, s30
	s_addc_u32 s35, s23, s31
	s_add_u32 s38, s34, 0x100
	s_addc_u32 s39, s35, 0
	s_add_u32 s36, s60, s30
	s_addc_u32 s37, s61, s31
	s_add_u32 s34, s34, 0x180
	s_addc_u32 s35, s35, 0
	s_cmpk_eq_i32 s30, 0xb00
	s_cselect_b32 s35, s59, s35
	s_cselect_b32 s34, s58, s34
	s_cselect_b32 s37, s21, s37
	s_cselect_b32 s36, s20, s36
	s_cselect_b32 s39, s17, s39
	s_cselect_b32 s38, s16, s38
	v_lshl_add_u64 v[200:201], v[130:131], 0, s[30:31]
	s_add_i32 m0, s3, 0xc000
	ds_read_b128 v[166:169], v206
	ds_read_b128 v[170:173], v206 offset:1024
	ds_read_b128 v[174:177], v206 offset:2048
	ds_read_b128 v[178:181], v206 offset:3072
	ds_read_b128 v[182:185], v206 offset:4096
	ds_read_b128 v[208:211], v206 offset:5120
	ds_read_b128 v[214:217], v206 offset:6144
	ds_read_b128 v[218:221], v206 offset:7168
	global_load_lds_dwordx4 v[200:201], off
	v_lshl_add_u64 v[200:201], v[132:133], 0, s[30:31]
	s_add_i32 m0, s3, 0xe000
	s_nop 0
	global_load_lds_dwordx4 v[200:201], off
	s_waitcnt vmcnt(8)
	s_waitcnt lgkmcnt(0)
	s_barrier
	s_waitcnt lgkmcnt(0)
	v_mfma_f32_16x16x32_bf16 v[126:129], v[134:137], v[166:169], v[126:129]
	v_mfma_f32_16x16x32_bf16 v[126:129], v[138:141], v[170:173], v[126:129]
	v_mfma_f32_16x16x32_bf16 v[110:113], v[138:141], v[178:181], v[110:113]
	v_mfma_f32_16x16x32_bf16 v[110:113], v[134:137], v[174:177], v[110:113]
	v_mfma_f32_16x16x32_bf16 v[94:97], v[134:137], v[182:185], v[94:97]
	v_mfma_f32_16x16x32_bf16 v[94:97], v[138:141], v[208:211], v[94:97]
	v_mfma_f32_16x16x32_bf16 v[78:81], v[138:141], v[218:221], v[78:81]
	v_mfma_f32_16x16x32_bf16 v[78:81], v[134:137], v[214:217], v[78:81]
	v_mfma_f32_16x16x32_bf16 v[74:77], v[142:145], v[214:217], v[74:77]
	v_mfma_f32_16x16x32_bf16 v[74:77], v[146:149], v[218:221], v[74:77]
	v_mfma_f32_16x16x32_bf16 v[90:93], v[146:149], v[208:211], v[90:93]
	v_mfma_f32_16x16x32_bf16 v[90:93], v[142:145], v[182:185], v[90:93]
	v_mfma_f32_16x16x32_bf16 v[106:109], v[142:145], v[174:177], v[106:109]
	v_mfma_f32_16x16x32_bf16 v[106:109], v[146:149], v[178:181], v[106:109]
	v_mfma_f32_16x16x32_bf16 v[122:125], v[146:149], v[170:173], v[122:125]
	v_mfma_f32_16x16x32_bf16 v[122:125], v[142:145], v[166:169], v[122:125]
	v_mfma_f32_16x16x32_bf16 v[118:121], v[150:153], v[166:169], v[118:121]
	v_mfma_f32_16x16x32_bf16 v[118:121], v[154:157], v[170:173], v[118:121]
	v_mfma_f32_16x16x32_bf16 v[102:105], v[154:157], v[178:181], v[102:105]
	v_mfma_f32_16x16x32_bf16 v[102:105], v[150:153], v[174:177], v[102:105]
	v_mfma_f32_16x16x32_bf16 v[86:89], v[150:153], v[182:185], v[86:89]
	v_mfma_f32_16x16x32_bf16 v[86:89], v[154:157], v[208:211], v[86:89]
	v_mfma_f32_16x16x32_bf16 v[70:73], v[154:157], v[218:221], v[70:73]
	v_mfma_f32_16x16x32_bf16 v[70:73], v[150:153], v[214:217], v[70:73]
	v_mfma_f32_16x16x32_bf16 v[66:69], v[158:161], v[214:217], v[66:69]
	v_mfma_f32_16x16x32_bf16 v[66:69], v[162:165], v[218:221], v[66:69]
	v_mfma_f32_16x16x32_bf16 v[82:85], v[162:165], v[208:211], v[82:85]
	v_mfma_f32_16x16x32_bf16 v[82:85], v[158:161], v[182:185], v[82:85]
	v_mfma_f32_16x16x32_bf16 v[98:101], v[158:161], v[174:177], v[98:101]
	v_mfma_f32_16x16x32_bf16 v[98:101], v[162:165], v[178:181], v[98:101]
	v_mfma_f32_16x16x32_bf16 v[114:117], v[162:165], v[170:173], v[114:117]
	v_mfma_f32_16x16x32_bf16 v[114:117], v[158:161], v[166:169], v[114:117]
	s_barrier
	s_add_i32 s63, s52, s2
	s_mov_b32 m0, s63
	ds_read_b128 v[166:169], v206 offset:16384
	ds_read_b128 v[170:173], v206 offset:17408
	ds_read_b128 v[174:177], v206 offset:18432
	ds_read_b128 v[178:181], v206 offset:19456
	ds_read_b128 v[182:185], v206 offset:20480
	ds_read_b128 v[208:211], v206 offset:21504
	ds_read_b128 v[214:217], v206 offset:22528
	ds_read_b128 v[218:221], v206 offset:23552
	global_load_lds_dwordx4 v188, s[36:37]
	s_add_i32 m0, s63, 0x2000
	s_add_u32 s64, s36, 0x68000
	s_addc_u32 s65, s37, 0
	s_add_i32 s63, s53, s2
	global_load_lds_dwordx4 v192, s[36:37]
	s_mov_b32 m0, s63
	s_nop 0
	global_load_lds_dwordx4 v188, s[64:65]
	s_add_i32 m0, s63, 0x2000
	s_nop 0
	global_load_lds_dwordx4 v192, s[64:65]
	s_mov_b32 m0, s3
	s_nop 0
	global_load_lds_dwordx4 v186, s[38:39]
	s_mov_b32 m0, s33
	s_nop 0
	global_load_lds_dwordx4 v190, s[38:39]
	s_waitcnt vmcnt(8)
	s_waitcnt lgkmcnt(0)
	s_barrier
	s_waitcnt lgkmcnt(0)
	v_mfma_f32_16x16x32_bf16 v[62:65], v[134:137], v[166:169], v[62:65]
	v_mfma_f32_16x16x32_bf16 v[62:65], v[138:141], v[170:173], v[62:65]
	v_mfma_f32_16x16x32_bf16 v[46:49], v[138:141], v[178:181], v[46:49]
	v_mfma_f32_16x16x32_bf16 v[46:49], v[134:137], v[174:177], v[46:49]
	v_mfma_f32_16x16x32_bf16 v[30:33], v[134:137], v[182:185], v[30:33]
	v_mfma_f32_16x16x32_bf16 v[30:33], v[138:141], v[208:211], v[30:33]
	v_mfma_f32_16x16x32_bf16 v[14:17], v[138:141], v[218:221], v[14:17]
	v_mfma_f32_16x16x32_bf16 v[14:17], v[134:137], v[214:217], v[14:17]
	v_mfma_f32_16x16x32_bf16 v[10:13], v[142:145], v[214:217], v[10:13]
	v_mfma_f32_16x16x32_bf16 v[10:13], v[146:149], v[218:221], v[10:13]
	v_mfma_f32_16x16x32_bf16 v[26:29], v[146:149], v[208:211], v[26:29]
	v_mfma_f32_16x16x32_bf16 v[26:29], v[142:145], v[182:185], v[26:29]
	v_mfma_f32_16x16x32_bf16 v[42:45], v[142:145], v[174:177], v[42:45]
	v_mfma_f32_16x16x32_bf16 v[42:45], v[146:149], v[178:181], v[42:45]
	v_mfma_f32_16x16x32_bf16 v[58:61], v[146:149], v[170:173], v[58:61]
	v_mfma_f32_16x16x32_bf16 v[58:61], v[142:145], v[166:169], v[58:61]
	v_mfma_f32_16x16x32_bf16 v[54:57], v[150:153], v[166:169], v[54:57]
	v_mfma_f32_16x16x32_bf16 v[54:57], v[154:157], v[170:173], v[54:57]
	v_mfma_f32_16x16x32_bf16 v[38:41], v[154:157], v[178:181], v[38:41]
	v_mfma_f32_16x16x32_bf16 v[38:41], v[150:153], v[174:177], v[38:41]
	v_mfma_f32_16x16x32_bf16 v[22:25], v[150:153], v[182:185], v[22:25]
	v_mfma_f32_16x16x32_bf16 v[22:25], v[154:157], v[208:211], v[22:25]
	v_mfma_f32_16x16x32_bf16 v[6:9], v[154:157], v[218:221], v[6:9]
	v_mfma_f32_16x16x32_bf16 v[6:9], v[150:153], v[214:217], v[6:9]
	v_mfma_f32_16x16x32_bf16 v[2:5], v[158:161], v[214:217], v[2:5]
	v_mfma_f32_16x16x32_bf16 v[2:5], v[162:165], v[218:221], v[2:5]
	v_mfma_f32_16x16x32_bf16 v[18:21], v[162:165], v[208:211], v[18:21]
	v_mfma_f32_16x16x32_bf16 v[18:21], v[158:161], v[182:185], v[18:21]
	v_mfma_f32_16x16x32_bf16 v[34:37], v[158:161], v[174:177], v[34:37]
	v_mfma_f32_16x16x32_bf16 v[34:37], v[162:165], v[178:181], v[34:37]
	v_mfma_f32_16x16x32_bf16 v[50:53], v[162:165], v[170:173], v[50:53]
	v_mfma_f32_16x16x32_bf16 v[50:53], v[158:161], v[166:169], v[50:53]
	s_barrier
	s_add_i32 s63, 0, 0x18000
	s_add_i32 s64, 0, 0x1c000
	v_add_u32_e32 v146, s63, v202
	v_add_u32_e32 v162, s64, v202
	ds_read_b128 v[134:137], v146
	ds_read_b128 v[138:141], v146 offset:1024
	ds_read_b128 v[142:145], v146 offset:2048
	ds_read_b128 v[146:149], v146 offset:3072
	ds_read_b128 v[150:153], v162
	ds_read_b128 v[154:157], v162 offset:1024
	ds_read_b128 v[158:161], v162 offset:2048
	ds_read_b128 v[162:165], v162 offset:3072
	s_add_u32 s38, s38, 0x188000
	s_addc_u32 s39, s39, 0
	s_mov_b32 m0, s40
	ds_read_b128 v[166:169], v206 offset:32768
	ds_read_b128 v[170:173], v206 offset:33792
	ds_read_b128 v[174:177], v206 offset:34816
	ds_read_b128 v[178:181], v206 offset:35840
	ds_read_b128 v[182:185], v206 offset:36864
	ds_read_b128 v[208:211], v206 offset:37888
	ds_read_b128 v[214:217], v206 offset:38912
	ds_read_b128 v[218:221], v206 offset:39936
	global_load_lds_dwordx4 v186, s[38:39]
	s_mov_b32 m0, s41
	s_nop 0
	global_load_lds_dwordx4 v190, s[38:39]
	s_waitcnt vmcnt(8)
	s_waitcnt lgkmcnt(0)
	s_barrier
	s_waitcnt lgkmcnt(0)
	v_mfma_f32_16x16x32_bf16 v[126:129], v[134:137], v[166:169], v[126:129]
	v_mfma_f32_16x16x32_bf16 v[126:129], v[138:141], v[170:173], v[126:129]
	v_mfma_f32_16x16x32_bf16 v[110:113], v[138:141], v[178:181], v[110:113]
	v_mfma_f32_16x16x32_bf16 v[110:113], v[134:137], v[174:177], v[110:113]
	v_mfma_f32_16x16x32_bf16 v[94:97], v[134:137], v[182:185], v[94:97]
	v_mfma_f32_16x16x32_bf16 v[94:97], v[138:141], v[208:211], v[94:97]
	v_mfma_f32_16x16x32_bf16 v[78:81], v[138:141], v[218:221], v[78:81]
	v_mfma_f32_16x16x32_bf16 v[78:81], v[134:137], v[214:217], v[78:81]
	v_mfma_f32_16x16x32_bf16 v[74:77], v[142:145], v[214:217], v[74:77]
	v_mfma_f32_16x16x32_bf16 v[74:77], v[146:149], v[218:221], v[74:77]
	v_mfma_f32_16x16x32_bf16 v[90:93], v[146:149], v[208:211], v[90:93]
	v_mfma_f32_16x16x32_bf16 v[90:93], v[142:145], v[182:185], v[90:93]
	v_mfma_f32_16x16x32_bf16 v[106:109], v[142:145], v[174:177], v[106:109]
	v_mfma_f32_16x16x32_bf16 v[106:109], v[146:149], v[178:181], v[106:109]
	v_mfma_f32_16x16x32_bf16 v[122:125], v[146:149], v[170:173], v[122:125]
	v_mfma_f32_16x16x32_bf16 v[122:125], v[142:145], v[166:169], v[122:125]
	v_mfma_f32_16x16x32_bf16 v[118:121], v[150:153], v[166:169], v[118:121]
	v_mfma_f32_16x16x32_bf16 v[118:121], v[154:157], v[170:173], v[118:121]
	v_mfma_f32_16x16x32_bf16 v[102:105], v[154:157], v[178:181], v[102:105]
	v_mfma_f32_16x16x32_bf16 v[102:105], v[150:153], v[174:177], v[102:105]
	v_mfma_f32_16x16x32_bf16 v[86:89], v[150:153], v[182:185], v[86:89]
	v_mfma_f32_16x16x32_bf16 v[86:89], v[154:157], v[208:211], v[86:89]
	v_mfma_f32_16x16x32_bf16 v[70:73], v[154:157], v[218:221], v[70:73]
	v_mfma_f32_16x16x32_bf16 v[70:73], v[150:153], v[214:217], v[70:73]
	v_mfma_f32_16x16x32_bf16 v[66:69], v[158:161], v[214:217], v[66:69]
	v_mfma_f32_16x16x32_bf16 v[66:69], v[162:165], v[218:221], v[66:69]
	v_mfma_f32_16x16x32_bf16 v[82:85], v[162:165], v[208:211], v[82:85]
	v_mfma_f32_16x16x32_bf16 v[82:85], v[158:161], v[182:185], v[82:85]
	v_mfma_f32_16x16x32_bf16 v[98:101], v[158:161], v[174:177], v[98:101]
	v_mfma_f32_16x16x32_bf16 v[98:101], v[162:165], v[178:181], v[98:101]
	v_mfma_f32_16x16x32_bf16 v[114:117], v[162:165], v[170:173], v[114:117]
	v_mfma_f32_16x16x32_bf16 v[114:117], v[158:161], v[166:169], v[114:117]
	s_barrier
	s_add_i32 s38, s63, s2
	s_add_u32 s36, s36, 0x80
	s_addc_u32 s37, s37, 0
	s_mov_b32 m0, s38
	ds_read_b128 v[166:169], v206 offset:49152
	ds_read_b128 v[170:173], v206 offset:50176
	ds_read_b128 v[174:177], v206 offset:51200
	ds_read_b128 v[178:181], v206 offset:52224
	ds_read_b128 v[182:185], v206 offset:53248
	ds_read_b128 v[208:211], v206 offset:54272
	ds_read_b128 v[214:217], v206 offset:55296
	ds_read_b128 v[218:221], v206 offset:56320
	global_load_lds_dwordx4 v188, s[36:37]
	s_add_i32 m0, s38, 0x2000
	s_add_i32 s38, s64, s2
	global_load_lds_dwordx4 v192, s[36:37]
	s_add_u32 s36, s36, 0x68000
	s_addc_u32 s37, s37, 0
	s_mov_b32 m0, s38
	s_nop 0
	global_load_lds_dwordx4 v188, s[36:37]
	s_add_i32 m0, s38, 0x2000
	s_nop 0
	global_load_lds_dwordx4 v192, s[36:37]
	s_mov_b32 m0, s50
	s_nop 0
	global_load_lds_dwordx4 v186, s[34:35]
	s_mov_b32 m0, s51
	s_nop 0
	global_load_lds_dwordx4 v190, s[34:35]
	s_waitcnt vmcnt(8)
	s_waitcnt lgkmcnt(0)
	s_barrier
	s_waitcnt lgkmcnt(0)
	v_mfma_f32_16x16x32_bf16 v[62:65], v[134:137], v[166:169], v[62:65]
	v_mfma_f32_16x16x32_bf16 v[62:65], v[138:141], v[170:173], v[62:65]
	v_mfma_f32_16x16x32_bf16 v[46:49], v[138:141], v[178:181], v[46:49]
	v_mfma_f32_16x16x32_bf16 v[46:49], v[134:137], v[174:177], v[46:49]
	v_mfma_f32_16x16x32_bf16 v[30:33], v[134:137], v[182:185], v[30:33]
	v_mfma_f32_16x16x32_bf16 v[30:33], v[138:141], v[208:211], v[30:33]
	v_mfma_f32_16x16x32_bf16 v[14:17], v[138:141], v[218:221], v[14:17]
	v_mfma_f32_16x16x32_bf16 v[14:17], v[134:137], v[214:217], v[14:17]
	v_mfma_f32_16x16x32_bf16 v[10:13], v[142:145], v[214:217], v[10:13]
	v_mfma_f32_16x16x32_bf16 v[10:13], v[146:149], v[218:221], v[10:13]
	v_mfma_f32_16x16x32_bf16 v[26:29], v[146:149], v[208:211], v[26:29]
	v_mfma_f32_16x16x32_bf16 v[26:29], v[142:145], v[182:185], v[26:29]
	v_mfma_f32_16x16x32_bf16 v[42:45], v[142:145], v[174:177], v[42:45]
	v_mfma_f32_16x16x32_bf16 v[42:45], v[146:149], v[178:181], v[42:45]
	v_mfma_f32_16x16x32_bf16 v[58:61], v[146:149], v[170:173], v[58:61]
	v_mfma_f32_16x16x32_bf16 v[58:61], v[142:145], v[166:169], v[58:61]
	v_mfma_f32_16x16x32_bf16 v[54:57], v[150:153], v[166:169], v[54:57]
	v_mfma_f32_16x16x32_bf16 v[54:57], v[154:157], v[170:173], v[54:57]
	v_mfma_f32_16x16x32_bf16 v[38:41], v[154:157], v[178:181], v[38:41]
	v_mfma_f32_16x16x32_bf16 v[38:41], v[150:153], v[174:177], v[38:41]
	v_mfma_f32_16x16x32_bf16 v[22:25], v[150:153], v[182:185], v[22:25]
	v_mfma_f32_16x16x32_bf16 v[22:25], v[154:157], v[208:211], v[22:25]
	v_mfma_f32_16x16x32_bf16 v[6:9], v[154:157], v[218:221], v[6:9]
	v_mfma_f32_16x16x32_bf16 v[6:9], v[150:153], v[214:217], v[6:9]
	v_mfma_f32_16x16x32_bf16 v[2:5], v[158:161], v[214:217], v[2:5]
	v_mfma_f32_16x16x32_bf16 v[2:5], v[162:165], v[218:221], v[2:5]
	v_mfma_f32_16x16x32_bf16 v[18:21], v[162:165], v[208:211], v[18:21]
	v_mfma_f32_16x16x32_bf16 v[18:21], v[158:161], v[182:185], v[18:21]
	v_mfma_f32_16x16x32_bf16 v[34:37], v[158:161], v[174:177], v[34:37]
	v_mfma_f32_16x16x32_bf16 v[34:37], v[162:165], v[178:181], v[34:37]
	v_mfma_f32_16x16x32_bf16 v[50:53], v[162:165], v[170:173], v[50:53]
	v_mfma_f32_16x16x32_bf16 v[50:53], v[158:161], v[166:169], v[50:53]
	s_barrier
	s_add_i32 s62, s62, 2
	s_add_u32 s30, s30, 0x100
	s_addc_u32 s31, s31, 0
	s_cmp_gt_u32 s62, 21
	s_cbranch_scc0 .LBB0_434
	s_and_b64 vcc, exec, s[14:15]
	s_cbranch_vccz .LBB0_437
	s_barrier

.LBB0_519:
	s_add_i32 s39, s56, 0xfffe8000
	s_and_b32 s38, s36, 0x100
	s_and_b32 s39, s39, 0x3e0000
	s_or_b32 s38, s38, s39
	s_add_u32 s57, s34, s38
	s_addc_u32 s59, s35, 0
	s_add_u32 s38, s36, 0x100
	s_addc_u32 s39, s37, 0
	s_add_i32 s41, s56, 0xffff8000
	s_and_b32 s40, s38, 0x100
	s_and_b32 s41, s41, 0x7e0000
	s_or_b32 s40, s41, s40
	s_add_u32 s40, s34, s40
	s_addc_u32 s41, s35, 0
	s_add_u32 s58, s53, s36
	s_addc_u32 s37, s54, s37
	s_add_i32 s42, s36, 0x180
	s_and_b32 s42, s42, 0x180
	s_and_b32 s43, s56, 0x7e0000
	s_or_b32 s42, s43, s42
	s_add_u32 s60, s34, s42
	s_addc_u32 s61, s35, 0
	s_cmpk_eq_i32 s36, 0x3f00
	s_cselect_b32 s43, s1, s41
	s_cselect_b32 s42, s21, s40
	s_cselect_b32 s41, s23, s37
	s_cselect_b32 s40, s22, s58
	s_cselect_b32 s37, s52, s61
	s_cselect_b32 s36, s31, s60
	s_add_i32 s60, 0, 0x10000
	v_add_u32_e32 v1, s60, v199
	ds_read_b128 v[130:133], v1
	ds_read_b128 v[134:137], v1 offset:1024
	ds_read_b128 v[138:141], v1 offset:2048
	ds_read_b128 v[142:145], v1 offset:3072
	ds_read_b128 v[146:149], v201
	ds_read_b128 v[150:153], v201 offset:1024
	ds_read_b128 v[154:157], v201 offset:2048
	ds_read_b128 v[158:161], v201 offset:3072
	s_add_u32 s58, s57, 0x10080
	s_addc_u32 s59, s59, 0
	s_add_i32 m0, s3, 0xc000
	ds_read_b128 v[162:165], v202
	ds_read_b128 v[166:169], v202 offset:1024
	ds_read_b128 v[170:173], v202 offset:2048
	ds_read_b128 v[174:177], v202 offset:3072
	ds_read_b128 v[186:189], v202 offset:4096
	ds_read_b128 v[190:193], v202 offset:5120
	ds_read_b128 v[194:197], v202 offset:6144
	ds_read_b128 v[204:207], v202 offset:7168
	global_load_lds_dwordx4 v178, s[58:59]
	s_add_i32 m0, s3, 0xe000
	s_nop 0
	global_load_lds_dwordx4 v182, s[58:59]
	s_waitcnt vmcnt(8)
	s_waitcnt lgkmcnt(0)
	s_barrier
	s_waitcnt lgkmcnt(0)
	v_mfma_f32_16x16x32_bf16 v[126:129], v[130:133], v[162:165], v[126:129]
	v_mfma_f32_16x16x32_bf16 v[126:129], v[134:137], v[166:169], v[126:129]
	v_mfma_f32_16x16x32_bf16 v[110:113], v[134:137], v[174:177], v[110:113]
	v_mfma_f32_16x16x32_bf16 v[110:113], v[130:133], v[170:173], v[110:113]
	v_mfma_f32_16x16x32_bf16 v[94:97], v[130:133], v[186:189], v[94:97]
	v_mfma_f32_16x16x32_bf16 v[94:97], v[134:137], v[190:193], v[94:97]
	v_mfma_f32_16x16x32_bf16 v[78:81], v[134:137], v[204:207], v[78:81]
	v_mfma_f32_16x16x32_bf16 v[78:81], v[130:133], v[194:197], v[78:81]
	v_mfma_f32_16x16x32_bf16 v[74:77], v[138:141], v[194:197], v[74:77]
	v_mfma_f32_16x16x32_bf16 v[74:77], v[142:145], v[204:207], v[74:77]
	v_mfma_f32_16x16x32_bf16 v[90:93], v[142:145], v[190:193], v[90:93]
	v_mfma_f32_16x16x32_bf16 v[90:93], v[138:141], v[186:189], v[90:93]
	v_mfma_f32_16x16x32_bf16 v[106:109], v[138:141], v[170:173], v[106:109]
	v_mfma_f32_16x16x32_bf16 v[106:109], v[142:145], v[174:177], v[106:109]
	v_mfma_f32_16x16x32_bf16 v[122:125], v[142:145], v[166:169], v[122:125]
	v_mfma_f32_16x16x32_bf16 v[122:125], v[138:141], v[162:165], v[122:125]
	v_mfma_f32_16x16x32_bf16 v[118:121], v[146:149], v[162:165], v[118:121]
	v_mfma_f32_16x16x32_bf16 v[118:121], v[150:153], v[166:169], v[118:121]
	v_mfma_f32_16x16x32_bf16 v[102:105], v[150:153], v[174:177], v[102:105]
	v_mfma_f32_16x16x32_bf16 v[102:105], v[146:149], v[170:173], v[102:105]
	v_mfma_f32_16x16x32_bf16 v[86:89], v[146:149], v[186:189], v[86:89]
	v_mfma_f32_16x16x32_bf16 v[86:89], v[150:153], v[190:193], v[86:89]
	v_mfma_f32_16x16x32_bf16 v[70:73], v[150:153], v[204:207], v[70:73]
	v_mfma_f32_16x16x32_bf16 v[70:73], v[146:149], v[194:197], v[70:73]
	v_mfma_f32_16x16x32_bf16 v[66:69], v[154:157], v[194:197], v[66:69]
	v_mfma_f32_16x16x32_bf16 v[66:69], v[158:161], v[204:207], v[66:69]
	v_mfma_f32_16x16x32_bf16 v[82:85], v[158:161], v[190:193], v[82:85]
	v_mfma_f32_16x16x32_bf16 v[82:85], v[154:157], v[186:189], v[82:85]
	v_mfma_f32_16x16x32_bf16 v[98:101], v[154:157], v[170:173], v[98:101]
	v_mfma_f32_16x16x32_bf16 v[98:101], v[158:161], v[174:177], v[98:101]
	v_mfma_f32_16x16x32_bf16 v[114:117], v[158:161], v[166:169], v[114:117]
	v_mfma_f32_16x16x32_bf16 v[114:117], v[154:157], v[162:165], v[114:117]
	s_barrier
	s_add_i32 s57, s60, s2
	v_lshl_add_u64 v[208:209], s[40:41], 0, v[180:181]
	s_mov_b32 m0, s57
	ds_read_b128 v[162:165], v202 offset:16384
	ds_read_b128 v[166:169], v202 offset:17408
	ds_read_b128 v[170:173], v202 offset:18432
	ds_read_b128 v[174:177], v202 offset:19456
	ds_read_b128 v[186:189], v202 offset:20480
	ds_read_b128 v[190:193], v202 offset:21504
	ds_read_b128 v[194:197], v202 offset:22528
	ds_read_b128 v[204:207], v202 offset:23552
	global_load_lds_dwordx4 v[208:209], off
	s_add_i32 m0, s57, 0x2000
	s_add_u32 s58, s40, 0x208000
	v_lshl_add_u64 v[210:211], s[40:41], 0, v[184:185]
	s_addc_u32 s59, s41, 0
	s_add_i32 s57, s49, s2
	global_load_lds_dwordx4 v[210:211], off
	s_mov_b32 m0, s57
	s_nop 0
	global_load_lds_dwordx4 v180, s[58:59]
	s_add_i32 m0, s57, 0x2000
	s_nop 0
	global_load_lds_dwordx4 v184, s[58:59]
	s_mov_b32 m0, s3
	s_nop 0
	global_load_lds_dwordx4 v178, s[42:43]
	s_mov_b32 m0, s33
	s_nop 0
	global_load_lds_dwordx4 v182, s[42:43]
	s_waitcnt vmcnt(8)
	s_waitcnt lgkmcnt(0)
	s_barrier
	s_waitcnt lgkmcnt(0)
	v_mfma_f32_16x16x32_bf16 v[62:65], v[130:133], v[162:165], v[62:65]
	v_mfma_f32_16x16x32_bf16 v[62:65], v[134:137], v[166:169], v[62:65]
	v_mfma_f32_16x16x32_bf16 v[46:49], v[134:137], v[174:177], v[46:49]
	v_mfma_f32_16x16x32_bf16 v[46:49], v[130:133], v[170:173], v[46:49]
	v_mfma_f32_16x16x32_bf16 v[30:33], v[130:133], v[186:189], v[30:33]
	v_mfma_f32_16x16x32_bf16 v[30:33], v[134:137], v[190:193], v[30:33]
	v_mfma_f32_16x16x32_bf16 v[14:17], v[134:137], v[204:207], v[14:17]
	v_mfma_f32_16x16x32_bf16 v[14:17], v[130:133], v[194:197], v[14:17]
	v_mfma_f32_16x16x32_bf16 v[10:13], v[138:141], v[194:197], v[10:13]
	v_mfma_f32_16x16x32_bf16 v[10:13], v[142:145], v[204:207], v[10:13]
	v_mfma_f32_16x16x32_bf16 v[26:29], v[142:145], v[190:193], v[26:29]
	v_mfma_f32_16x16x32_bf16 v[26:29], v[138:141], v[186:189], v[26:29]
	v_mfma_f32_16x16x32_bf16 v[42:45], v[138:141], v[170:173], v[42:45]
	v_mfma_f32_16x16x32_bf16 v[42:45], v[142:145], v[174:177], v[42:45]
	v_mfma_f32_16x16x32_bf16 v[58:61], v[142:145], v[166:169], v[58:61]
	v_mfma_f32_16x16x32_bf16 v[58:61], v[138:141], v[162:165], v[58:61]
	v_mfma_f32_16x16x32_bf16 v[54:57], v[146:149], v[162:165], v[54:57]
	v_mfma_f32_16x16x32_bf16 v[54:57], v[150:153], v[166:169], v[54:57]
	v_mfma_f32_16x16x32_bf16 v[38:41], v[150:153], v[174:177], v[38:41]
	v_mfma_f32_16x16x32_bf16 v[38:41], v[146:149], v[170:173], v[38:41]
	v_mfma_f32_16x16x32_bf16 v[22:25], v[146:149], v[186:189], v[22:25]
	v_mfma_f32_16x16x32_bf16 v[22:25], v[150:153], v[190:193], v[22:25]
	v_mfma_f32_16x16x32_bf16 v[6:9], v[150:153], v[204:207], v[6:9]
	v_mfma_f32_16x16x32_bf16 v[6:9], v[146:149], v[194:197], v[6:9]
	v_mfma_f32_16x16x32_bf16 v[2:5], v[154:157], v[194:197], v[2:5]
	v_mfma_f32_16x16x32_bf16 v[2:5], v[158:161], v[204:207], v[2:5]
	v_mfma_f32_16x16x32_bf16 v[18:21], v[158:161], v[190:193], v[18:21]
	v_mfma_f32_16x16x32_bf16 v[18:21], v[154:157], v[186:189], v[18:21]
	v_mfma_f32_16x16x32_bf16 v[34:37], v[154:157], v[170:173], v[34:37]
	v_mfma_f32_16x16x32_bf16 v[34:37], v[158:161], v[174:177], v[34:37]
	v_mfma_f32_16x16x32_bf16 v[50:53], v[158:161], v[166:169], v[50:53]
	v_mfma_f32_16x16x32_bf16 v[50:53], v[154:157], v[162:165], v[50:53]
	s_barrier
	s_add_i32 s57, 0, 0x18000
	v_add_u32_e32 v1, s57, v199
	s_add_i32 s58, 0, 0x1c000
	ds_read_b128 v[130:133], v1
	ds_read_b128 v[134:137], v1 offset:1024
	ds_read_b128 v[138:141], v1 offset:2048
	ds_read_b128 v[142:145], v1 offset:3072
	v_add_u32_e32 v1, s58, v199
	ds_read_b128 v[146:149], v1
	ds_read_b128 v[150:153], v1 offset:1024
	ds_read_b128 v[154:157], v1 offset:2048
	ds_read_b128 v[158:161], v1 offset:3072
	s_add_u32 s42, s42, 0x10000
	s_addc_u32 s43, s43, 0
	s_mov_b32 m0, s44
	ds_read_b128 v[162:165], v202 offset:32768
	ds_read_b128 v[166:169], v202 offset:33792
	ds_read_b128 v[170:173], v202 offset:34816
	ds_read_b128 v[174:177], v202 offset:35840
	ds_read_b128 v[186:189], v202 offset:36864
	ds_read_b128 v[190:193], v202 offset:37888
	ds_read_b128 v[194:197], v202 offset:38912
	ds_read_b128 v[204:207], v202 offset:39936
	global_load_lds_dwordx4 v178, s[42:43]
	v_lshl_add_u64 v[214:215], s[42:43], 0, v[182:183]
	s_mov_b32 m0, s45
	s_nop 0
	global_load_lds_dwordx4 v[214:215], off
	s_waitcnt vmcnt(8)
	s_waitcnt lgkmcnt(0)
	s_barrier
	s_waitcnt lgkmcnt(0)
	v_mfma_f32_16x16x32_bf16 v[126:129], v[130:133], v[162:165], v[126:129]
	v_mfma_f32_16x16x32_bf16 v[126:129], v[134:137], v[166:169], v[126:129]
	v_mfma_f32_16x16x32_bf16 v[110:113], v[134:137], v[174:177], v[110:113]
	v_mfma_f32_16x16x32_bf16 v[110:113], v[130:133], v[170:173], v[110:113]
	v_mfma_f32_16x16x32_bf16 v[94:97], v[130:133], v[186:189], v[94:97]
	v_mfma_f32_16x16x32_bf16 v[94:97], v[134:137], v[190:193], v[94:97]
	v_mfma_f32_16x16x32_bf16 v[78:81], v[134:137], v[204:207], v[78:81]
	v_mfma_f32_16x16x32_bf16 v[78:81], v[130:133], v[194:197], v[78:81]
	v_mfma_f32_16x16x32_bf16 v[74:77], v[138:141], v[194:197], v[74:77]
	v_mfma_f32_16x16x32_bf16 v[74:77], v[142:145], v[204:207], v[74:77]
	v_mfma_f32_16x16x32_bf16 v[90:93], v[142:145], v[190:193], v[90:93]
	v_mfma_f32_16x16x32_bf16 v[90:93], v[138:141], v[186:189], v[90:93]
	v_mfma_f32_16x16x32_bf16 v[106:109], v[138:141], v[170:173], v[106:109]
	v_mfma_f32_16x16x32_bf16 v[106:109], v[142:145], v[174:177], v[106:109]
	v_mfma_f32_16x16x32_bf16 v[122:125], v[142:145], v[166:169], v[122:125]
	v_mfma_f32_16x16x32_bf16 v[122:125], v[138:141], v[162:165], v[122:125]
	v_mfma_f32_16x16x32_bf16 v[118:121], v[146:149], v[162:165], v[118:121]
	v_mfma_f32_16x16x32_bf16 v[118:121], v[150:153], v[166:169], v[118:121]
	v_mfma_f32_16x16x32_bf16 v[102:105], v[150:153], v[174:177], v[102:105]
	v_mfma_f32_16x16x32_bf16 v[102:105], v[146:149], v[170:173], v[102:105]
	v_mfma_f32_16x16x32_bf16 v[86:89], v[146:149], v[186:189], v[86:89]
	v_mfma_f32_16x16x32_bf16 v[86:89], v[150:153], v[190:193], v[86:89]
	v_mfma_f32_16x16x32_bf16 v[70:73], v[150:153], v[204:207], v[70:73]
	v_mfma_f32_16x16x32_bf16 v[70:73], v[146:149], v[194:197], v[70:73]
	v_mfma_f32_16x16x32_bf16 v[66:69], v[154:157], v[194:197], v[66:69]
	v_mfma_f32_16x16x32_bf16 v[66:69], v[158:161], v[204:207], v[66:69]
	v_mfma_f32_16x16x32_bf16 v[82:85], v[158:161], v[190:193], v[82:85]
	v_mfma_f32_16x16x32_bf16 v[82:85], v[154:157], v[186:189], v[82:85]
	v_mfma_f32_16x16x32_bf16 v[98:101], v[154:157], v[170:173], v[98:101]
	v_mfma_f32_16x16x32_bf16 v[98:101], v[158:161], v[174:177], v[98:101]
	v_mfma_f32_16x16x32_bf16 v[114:117], v[158:161], v[166:169], v[114:117]
	v_mfma_f32_16x16x32_bf16 v[114:117], v[154:157], v[162:165], v[114:117]
	s_barrier
	s_add_i32 s42, s57, s2
	v_lshl_add_u64 v[208:209], v[208:209], 0, s[16:17]
	s_mov_b32 m0, s42
	ds_read_b128 v[162:165], v202 offset:49152
	ds_read_b128 v[166:169], v202 offset:50176
	ds_read_b128 v[170:173], v202 offset:51200
	ds_read_b128 v[174:177], v202 offset:52224
	ds_read_b128 v[186:189], v202 offset:53248
	ds_read_b128 v[190:193], v202 offset:54272
	ds_read_b128 v[194:197], v202 offset:55296
	ds_read_b128 v[204:207], v202 offset:56320
	global_load_lds_dwordx4 v[208:209], off
	s_add_i32 m0, s42, 0x2000
	s_add_u32 s40, s40, 0x208080
	v_lshl_add_u64 v[208:209], v[210:211], 0, s[16:17]
	s_addc_u32 s41, s41, 0
	s_add_i32 s42, s58, s2
	global_load_lds_dwordx4 v[208:209], off
	s_mov_b32 m0, s42
	s_nop 0
	global_load_lds_dwordx4 v180, s[40:41]
	s_add_i32 m0, s42, 0x2000
	s_nop 0
	global_load_lds_dwordx4 v184, s[40:41]
	s_mov_b32 m0, s47
	s_nop 0
	global_load_lds_dwordx4 v178, s[36:37]
	v_lshl_add_u64 v[208:209], s[36:37], 0, v[182:183]
	s_mov_b32 m0, s48
	s_nop 0
	global_load_lds_dwordx4 v[208:209], off
	s_waitcnt vmcnt(8)
	s_waitcnt lgkmcnt(0)
	s_barrier
	s_waitcnt lgkmcnt(0)
	v_mfma_f32_16x16x32_bf16 v[62:65], v[130:133], v[162:165], v[62:65]
	v_mfma_f32_16x16x32_bf16 v[62:65], v[134:137], v[166:169], v[62:65]
	v_mfma_f32_16x16x32_bf16 v[46:49], v[134:137], v[174:177], v[46:49]
	v_mfma_f32_16x16x32_bf16 v[46:49], v[130:133], v[170:173], v[46:49]
	v_mfma_f32_16x16x32_bf16 v[30:33], v[130:133], v[186:189], v[30:33]
	v_mfma_f32_16x16x32_bf16 v[30:33], v[134:137], v[190:193], v[30:33]
	v_mfma_f32_16x16x32_bf16 v[14:17], v[134:137], v[204:207], v[14:17]
	v_mfma_f32_16x16x32_bf16 v[14:17], v[130:133], v[194:197], v[14:17]
	v_mfma_f32_16x16x32_bf16 v[10:13], v[138:141], v[194:197], v[10:13]
	v_mfma_f32_16x16x32_bf16 v[10:13], v[142:145], v[204:207], v[10:13]
	v_mfma_f32_16x16x32_bf16 v[26:29], v[142:145], v[190:193], v[26:29]
	v_mfma_f32_16x16x32_bf16 v[26:29], v[138:141], v[186:189], v[26:29]
	v_mfma_f32_16x16x32_bf16 v[42:45], v[138:141], v[170:173], v[42:45]
	v_mfma_f32_16x16x32_bf16 v[42:45], v[142:145], v[174:177], v[42:45]
	v_mfma_f32_16x16x32_bf16 v[58:61], v[142:145], v[166:169], v[58:61]
	v_mfma_f32_16x16x32_bf16 v[58:61], v[138:141], v[162:165], v[58:61]
	v_mfma_f32_16x16x32_bf16 v[54:57], v[146:149], v[162:165], v[54:57]
	v_mfma_f32_16x16x32_bf16 v[54:57], v[150:153], v[166:169], v[54:57]
	v_mfma_f32_16x16x32_bf16 v[38:41], v[150:153], v[174:177], v[38:41]
	v_mfma_f32_16x16x32_bf16 v[38:41], v[146:149], v[170:173], v[38:41]
	v_mfma_f32_16x16x32_bf16 v[22:25], v[146:149], v[186:189], v[22:25]
	v_mfma_f32_16x16x32_bf16 v[22:25], v[150:153], v[190:193], v[22:25]
	v_mfma_f32_16x16x32_bf16 v[6:9], v[150:153], v[204:207], v[6:9]
	v_mfma_f32_16x16x32_bf16 v[6:9], v[146:149], v[194:197], v[6:9]
	v_mfma_f32_16x16x32_bf16 v[2:5], v[154:157], v[194:197], v[2:5]
	v_mfma_f32_16x16x32_bf16 v[2:5], v[158:161], v[204:207], v[2:5]
	v_mfma_f32_16x16x32_bf16 v[18:21], v[158:161], v[190:193], v[18:21]
	v_mfma_f32_16x16x32_bf16 v[18:21], v[154:157], v[186:189], v[18:21]
	v_mfma_f32_16x16x32_bf16 v[34:37], v[154:157], v[170:173], v[34:37]
	v_mfma_f32_16x16x32_bf16 v[34:37], v[158:161], v[174:177], v[34:37]
	v_mfma_f32_16x16x32_bf16 v[50:53], v[158:161], v[166:169], v[50:53]
	v_mfma_f32_16x16x32_bf16 v[50:53], v[154:157], v[162:165], v[50:53]
	s_barrier
	s_add_i32 s55, s55, 2
	s_add_i32 s56, s56, 0x10000
	s_cmpk_gt_u32 s55, 0x7d
	s_mov_b64 s[36:37], s[38:39]
	s_cbranch_scc0 .LBB0_519
	s_and_b64 vcc, exec, s[18:19]
	s_cbranch_vccz .LBB0_522
	s_barrier

.LBB0_612:
	ds_read_b128 v[166:169], v152
	ds_read_b128 v[170:173], v152 offset:1024
	ds_read_b128 v[174:177], v152 offset:2048
	ds_read_b128 v[178:181], v152 offset:3072
	ds_read_b128 v[182:185], v153
	ds_read_b128 v[186:189], v153 offset:1024
	ds_read_b128 v[190:193], v153 offset:2048
	ds_read_b128 v[194:197], v153 offset:3072
	s_add_u32 s26, s4, s22
	s_addc_u32 s27, s5, s23
	s_add_u32 s30, s26, 0x100
	s_addc_u32 s31, s27, 0
	s_add_u32 s28, s52, s22
	s_addc_u32 s29, s53, s23
	s_add_u32 s26, s26, 0x180
	s_addc_u32 s27, s27, 0
	s_cmpk_eq_i32 s22, 0x1f00
	s_cselect_b32 s27, s51, s27
	s_cselect_b32 s26, s50, s26
	s_cselect_b32 s29, s21, s29
	s_cselect_b32 s28, s20, s28
	s_cselect_b32 s31, s19, s31
	s_cselect_b32 s30, s18, s30
	s_mov_b32 m0, s37
	v_lshl_add_u64 v[210:211], v[148:149], 0, s[22:23]
	ds_read_b128 v[198:201], v154
	ds_read_b128 v[202:205], v154 offset:1024
	ds_read_b128 v[206:209], v154 offset:2048
	ds_read_b128 v[214:217], v154 offset:3072
	ds_read_b128 v[218:221], v154 offset:4096
	ds_read_b128 v[222:225], v154 offset:5120
	ds_read_b128 v[226:229], v154 offset:6144
	ds_read_b128 v[230:233], v154 offset:7168
	global_load_lds_dwordx4 v[210:211], off
	v_lshl_add_u64 v[210:211], v[150:151], 0, s[22:23]
	s_mov_b32 m0, s38
	s_nop 0
	global_load_lds_dwordx4 v[210:211], off
	s_waitcnt vmcnt(8)
	s_waitcnt lgkmcnt(0)
	s_barrier
	s_waitcnt lgkmcnt(0)
	v_mfma_f32_16x16x32_bf16 v[126:129], v[166:169], v[198:201], v[126:129]
	v_mfma_f32_16x16x32_bf16 v[126:129], v[170:173], v[202:205], v[126:129]
	v_mfma_f32_16x16x32_bf16 v[110:113], v[170:173], v[214:217], v[110:113]
	v_mfma_f32_16x16x32_bf16 v[110:113], v[166:169], v[206:209], v[110:113]
	v_mfma_f32_16x16x32_bf16 v[94:97], v[166:169], v[218:221], v[94:97]
	v_mfma_f32_16x16x32_bf16 v[94:97], v[170:173], v[222:225], v[94:97]
	v_mfma_f32_16x16x32_bf16 v[78:81], v[170:173], v[230:233], v[78:81]
	v_mfma_f32_16x16x32_bf16 v[78:81], v[166:169], v[226:229], v[78:81]
	v_mfma_f32_16x16x32_bf16 v[74:77], v[174:177], v[226:229], v[74:77]
	v_mfma_f32_16x16x32_bf16 v[74:77], v[178:181], v[230:233], v[74:77]
	v_mfma_f32_16x16x32_bf16 v[90:93], v[178:181], v[222:225], v[90:93]
	v_mfma_f32_16x16x32_bf16 v[90:93], v[174:177], v[218:221], v[90:93]
	v_mfma_f32_16x16x32_bf16 v[106:109], v[174:177], v[206:209], v[106:109]
	v_mfma_f32_16x16x32_bf16 v[106:109], v[178:181], v[214:217], v[106:109]
	v_mfma_f32_16x16x32_bf16 v[122:125], v[178:181], v[202:205], v[122:125]
	v_mfma_f32_16x16x32_bf16 v[122:125], v[174:177], v[198:201], v[122:125]
	v_mfma_f32_16x16x32_bf16 v[118:121], v[182:185], v[198:201], v[118:121]
	v_mfma_f32_16x16x32_bf16 v[118:121], v[186:189], v[202:205], v[118:121]
	v_mfma_f32_16x16x32_bf16 v[102:105], v[186:189], v[214:217], v[102:105]
	v_mfma_f32_16x16x32_bf16 v[102:105], v[182:185], v[206:209], v[102:105]
	v_mfma_f32_16x16x32_bf16 v[86:89], v[182:185], v[218:221], v[86:89]
	v_mfma_f32_16x16x32_bf16 v[86:89], v[186:189], v[222:225], v[86:89]
	v_mfma_f32_16x16x32_bf16 v[70:73], v[186:189], v[230:233], v[70:73]
	v_mfma_f32_16x16x32_bf16 v[70:73], v[182:185], v[226:229], v[70:73]
	v_mfma_f32_16x16x32_bf16 v[66:69], v[190:193], v[226:229], v[66:69]
	v_mfma_f32_16x16x32_bf16 v[66:69], v[194:197], v[230:233], v[66:69]
	v_mfma_f32_16x16x32_bf16 v[82:85], v[194:197], v[222:225], v[82:85]
	v_mfma_f32_16x16x32_bf16 v[82:85], v[190:193], v[218:221], v[82:85]
	v_mfma_f32_16x16x32_bf16 v[98:101], v[190:193], v[206:209], v[98:101]
	v_mfma_f32_16x16x32_bf16 v[98:101], v[194:197], v[214:217], v[98:101]
	v_mfma_f32_16x16x32_bf16 v[114:117], v[194:197], v[202:205], v[114:117]
	v_mfma_f32_16x16x32_bf16 v[114:117], v[190:193], v[198:201], v[114:117]
	s_barrier
	s_mov_b32 m0, s39
	s_add_u32 s56, s28, 0x108000
	ds_read_b128 v[198:201], v154 offset:16384
	ds_read_b128 v[202:205], v154 offset:17408
	ds_read_b128 v[206:209], v154 offset:18432
	ds_read_b128 v[214:217], v154 offset:19456
	ds_read_b128 v[218:221], v154 offset:20480
	ds_read_b128 v[222:225], v154 offset:21504
	ds_read_b128 v[226:229], v154 offset:22528
	ds_read_b128 v[230:233], v154 offset:23552
	global_load_lds_dwordx4 v132, s[28:29]
	s_mov_b32 m0, s40
	s_addc_u32 s57, s29, 0
	global_load_lds_dwordx4 v136, s[28:29]
	s_mov_b32 m0, s41
	s_nop 0
	global_load_lds_dwordx4 v132, s[56:57]
	s_mov_b32 m0, s42
	s_nop 0
	global_load_lds_dwordx4 v136, s[56:57]
	s_mov_b32 m0, s2
	s_nop 0
	global_load_lds_dwordx4 v130, s[30:31]
	s_mov_b32 m0, s3
	s_nop 0
	global_load_lds_dwordx4 v134, s[30:31]
	s_waitcnt vmcnt(8)
	s_waitcnt lgkmcnt(0)
	s_barrier
	s_waitcnt lgkmcnt(0)
	v_mfma_f32_16x16x32_bf16 v[62:65], v[166:169], v[198:201], v[62:65]
	v_mfma_f32_16x16x32_bf16 v[62:65], v[170:173], v[202:205], v[62:65]
	v_mfma_f32_16x16x32_bf16 v[46:49], v[170:173], v[214:217], v[46:49]
	v_mfma_f32_16x16x32_bf16 v[46:49], v[166:169], v[206:209], v[46:49]
	v_mfma_f32_16x16x32_bf16 v[30:33], v[166:169], v[218:221], v[30:33]
	v_mfma_f32_16x16x32_bf16 v[30:33], v[170:173], v[222:225], v[30:33]
	v_mfma_f32_16x16x32_bf16 v[14:17], v[170:173], v[230:233], v[14:17]
	v_mfma_f32_16x16x32_bf16 v[14:17], v[166:169], v[226:229], v[14:17]
	v_mfma_f32_16x16x32_bf16 v[10:13], v[174:177], v[226:229], v[10:13]
	v_mfma_f32_16x16x32_bf16 v[10:13], v[178:181], v[230:233], v[10:13]
	v_mfma_f32_16x16x32_bf16 v[26:29], v[178:181], v[222:225], v[26:29]
	v_mfma_f32_16x16x32_bf16 v[26:29], v[174:177], v[218:221], v[26:29]
	v_mfma_f32_16x16x32_bf16 v[42:45], v[174:177], v[206:209], v[42:45]
	v_mfma_f32_16x16x32_bf16 v[42:45], v[178:181], v[214:217], v[42:45]
	v_mfma_f32_16x16x32_bf16 v[58:61], v[178:181], v[202:205], v[58:61]
	v_mfma_f32_16x16x32_bf16 v[58:61], v[174:177], v[198:201], v[58:61]
	v_mfma_f32_16x16x32_bf16 v[54:57], v[182:185], v[198:201], v[54:57]
	v_mfma_f32_16x16x32_bf16 v[54:57], v[186:189], v[202:205], v[54:57]
	v_mfma_f32_16x16x32_bf16 v[38:41], v[186:189], v[214:217], v[38:41]
	v_mfma_f32_16x16x32_bf16 v[38:41], v[182:185], v[206:209], v[38:41]
	v_mfma_f32_16x16x32_bf16 v[22:25], v[182:185], v[218:221], v[22:25]
	v_mfma_f32_16x16x32_bf16 v[22:25], v[186:189], v[222:225], v[22:25]
	v_mfma_f32_16x16x32_bf16 v[6:9], v[186:189], v[230:233], v[6:9]
	v_mfma_f32_16x16x32_bf16 v[6:9], v[182:185], v[226:229], v[6:9]
	v_mfma_f32_16x16x32_bf16 v[2:5], v[190:193], v[226:229], v[2:5]
	v_mfma_f32_16x16x32_bf16 v[2:5], v[194:197], v[230:233], v[2:5]
	v_mfma_f32_16x16x32_bf16 v[18:21], v[194:197], v[222:225], v[18:21]
	v_mfma_f32_16x16x32_bf16 v[18:21], v[190:193], v[218:221], v[18:21]
	v_mfma_f32_16x16x32_bf16 v[34:37], v[190:193], v[206:209], v[34:37]
	v_mfma_f32_16x16x32_bf16 v[34:37], v[194:197], v[214:217], v[34:37]
	v_mfma_f32_16x16x32_bf16 v[50:53], v[194:197], v[202:205], v[50:53]
	v_mfma_f32_16x16x32_bf16 v[50:53], v[190:193], v[198:201], v[50:53]
	s_barrier
	ds_read_b128 v[166:169], v156
	ds_read_b128 v[170:173], v156 offset:1024
	ds_read_b128 v[174:177], v156 offset:2048
	ds_read_b128 v[178:181], v156 offset:3072
	ds_read_b128 v[182:185], v157
	ds_read_b128 v[186:189], v157 offset:1024
	ds_read_b128 v[190:193], v157 offset:2048
	ds_read_b128 v[194:197], v157 offset:3072
	s_add_u32 s30, s30, 0x108000
	s_addc_u32 s31, s31, 0
	s_mov_b32 m0, s33
	ds_read_b128 v[198:201], v154 offset:32768
	ds_read_b128 v[202:205], v154 offset:33792
	ds_read_b128 v[206:209], v154 offset:34816
	ds_read_b128 v[214:217], v154 offset:35840
	ds_read_b128 v[218:221], v154 offset:36864
	ds_read_b128 v[222:225], v154 offset:37888
	ds_read_b128 v[226:229], v154 offset:38912
	ds_read_b128 v[230:233], v154 offset:39936
	global_load_lds_dwordx4 v130, s[30:31]
	s_mov_b32 m0, s34
	s_nop 0
	global_load_lds_dwordx4 v134, s[30:31]
	s_waitcnt vmcnt(8)
	s_waitcnt lgkmcnt(0)
	s_barrier
	s_waitcnt lgkmcnt(0)
	v_mfma_f32_16x16x32_bf16 v[126:129], v[166:169], v[198:201], v[126:129]
	v_mfma_f32_16x16x32_bf16 v[126:129], v[170:173], v[202:205], v[126:129]
	v_mfma_f32_16x16x32_bf16 v[110:113], v[170:173], v[214:217], v[110:113]
	v_mfma_f32_16x16x32_bf16 v[110:113], v[166:169], v[206:209], v[110:113]
	v_mfma_f32_16x16x32_bf16 v[94:97], v[166:169], v[218:221], v[94:97]
	v_mfma_f32_16x16x32_bf16 v[94:97], v[170:173], v[222:225], v[94:97]
	v_mfma_f32_16x16x32_bf16 v[78:81], v[170:173], v[230:233], v[78:81]
	v_mfma_f32_16x16x32_bf16 v[78:81], v[166:169], v[226:229], v[78:81]
	v_mfma_f32_16x16x32_bf16 v[74:77], v[174:177], v[226:229], v[74:77]
	v_mfma_f32_16x16x32_bf16 v[74:77], v[178:181], v[230:233], v[74:77]
	v_mfma_f32_16x16x32_bf16 v[90:93], v[178:181], v[222:225], v[90:93]
	v_mfma_f32_16x16x32_bf16 v[90:93], v[174:177], v[218:221], v[90:93]
	v_mfma_f32_16x16x32_bf16 v[106:109], v[174:177], v[206:209], v[106:109]
	v_mfma_f32_16x16x32_bf16 v[106:109], v[178:181], v[214:217], v[106:109]
	v_mfma_f32_16x16x32_bf16 v[122:125], v[178:181], v[202:205], v[122:125]
	v_mfma_f32_16x16x32_bf16 v[122:125], v[174:177], v[198:201], v[122:125]
	v_mfma_f32_16x16x32_bf16 v[118:121], v[182:185], v[198:201], v[118:121]
	v_mfma_f32_16x16x32_bf16 v[118:121], v[186:189], v[202:205], v[118:121]
	v_mfma_f32_16x16x32_bf16 v[102:105], v[186:189], v[214:217], v[102:105]
	v_mfma_f32_16x16x32_bf16 v[102:105], v[182:185], v[206:209], v[102:105]
	v_mfma_f32_16x16x32_bf16 v[86:89], v[182:185], v[218:221], v[86:89]
	v_mfma_f32_16x16x32_bf16 v[86:89], v[186:189], v[222:225], v[86:89]
	v_mfma_f32_16x16x32_bf16 v[70:73], v[186:189], v[230:233], v[70:73]
	v_mfma_f32_16x16x32_bf16 v[70:73], v[182:185], v[226:229], v[70:73]
	v_mfma_f32_16x16x32_bf16 v[66:69], v[190:193], v[226:229], v[66:69]
	v_mfma_f32_16x16x32_bf16 v[66:69], v[194:197], v[230:233], v[66:69]
	v_mfma_f32_16x16x32_bf16 v[82:85], v[194:197], v[222:225], v[82:85]
	v_mfma_f32_16x16x32_bf16 v[82:85], v[190:193], v[218:221], v[82:85]
	v_mfma_f32_16x16x32_bf16 v[98:101], v[190:193], v[206:209], v[98:101]
	v_mfma_f32_16x16x32_bf16 v[98:101], v[194:197], v[214:217], v[98:101]
	v_mfma_f32_16x16x32_bf16 v[114:117], v[194:197], v[202:205], v[114:117]
	v_mfma_f32_16x16x32_bf16 v[114:117], v[190:193], v[198:201], v[114:117]
	s_barrier
	s_mov_b32 m0, s43
	s_add_u32 s28, s28, 0x80
	s_addc_u32 s29, s29, 0
	ds_read_b128 v[198:201], v154 offset:49152
	ds_read_b128 v[202:205], v154 offset:50176
	ds_read_b128 v[206:209], v154 offset:51200
	ds_read_b128 v[214:217], v154 offset:52224
	ds_read_b128 v[218:221], v154 offset:53248
	ds_read_b128 v[222:225], v154 offset:54272
	ds_read_b128 v[226:229], v154 offset:55296
	ds_read_b128 v[230:233], v154 offset:56320
	global_load_lds_dwordx4 v132, s[28:29]
	s_mov_b32 m0, s44
	s_nop 0
	global_load_lds_dwordx4 v136, s[28:29]
	s_add_u32 s28, s28, 0x108000
	s_addc_u32 s29, s29, 0
	s_mov_b32 m0, s45
	s_nop 0
	global_load_lds_dwordx4 v132, s[28:29]
	s_mov_b32 m0, s46
	s_nop 0
	global_load_lds_dwordx4 v136, s[28:29]
	s_mov_b32 m0, s35
	s_nop 0
	global_load_lds_dwordx4 v130, s[26:27]
	s_mov_b32 m0, s36
	s_nop 0
	global_load_lds_dwordx4 v134, s[26:27]
	s_waitcnt vmcnt(8)
	s_waitcnt lgkmcnt(0)
	s_barrier
	s_waitcnt lgkmcnt(0)
	v_mfma_f32_16x16x32_bf16 v[62:65], v[166:169], v[198:201], v[62:65]
	v_mfma_f32_16x16x32_bf16 v[62:65], v[170:173], v[202:205], v[62:65]
	v_mfma_f32_16x16x32_bf16 v[46:49], v[170:173], v[214:217], v[46:49]
	v_mfma_f32_16x16x32_bf16 v[46:49], v[166:169], v[206:209], v[46:49]
	v_mfma_f32_16x16x32_bf16 v[30:33], v[166:169], v[218:221], v[30:33]
	v_mfma_f32_16x16x32_bf16 v[30:33], v[170:173], v[222:225], v[30:33]
	v_mfma_f32_16x16x32_bf16 v[14:17], v[170:173], v[230:233], v[14:17]
	v_mfma_f32_16x16x32_bf16 v[14:17], v[166:169], v[226:229], v[14:17]
	v_mfma_f32_16x16x32_bf16 v[10:13], v[174:177], v[226:229], v[10:13]
	v_mfma_f32_16x16x32_bf16 v[10:13], v[178:181], v[230:233], v[10:13]
	v_mfma_f32_16x16x32_bf16 v[26:29], v[178:181], v[222:225], v[26:29]
	v_mfma_f32_16x16x32_bf16 v[26:29], v[174:177], v[218:221], v[26:29]
	v_mfma_f32_16x16x32_bf16 v[42:45], v[174:177], v[206:209], v[42:45]
	v_mfma_f32_16x16x32_bf16 v[42:45], v[178:181], v[214:217], v[42:45]
	v_mfma_f32_16x16x32_bf16 v[58:61], v[178:181], v[202:205], v[58:61]
	v_mfma_f32_16x16x32_bf16 v[58:61], v[174:177], v[198:201], v[58:61]
	v_mfma_f32_16x16x32_bf16 v[54:57], v[182:185], v[198:201], v[54:57]
	v_mfma_f32_16x16x32_bf16 v[54:57], v[186:189], v[202:205], v[54:57]
	v_mfma_f32_16x16x32_bf16 v[38:41], v[186:189], v[214:217], v[38:41]
	v_mfma_f32_16x16x32_bf16 v[38:41], v[182:185], v[206:209], v[38:41]
	v_mfma_f32_16x16x32_bf16 v[22:25], v[182:185], v[218:221], v[22:25]
	v_mfma_f32_16x16x32_bf16 v[22:25], v[186:189], v[222:225], v[22:25]
	v_mfma_f32_16x16x32_bf16 v[6:9], v[186:189], v[230:233], v[6:9]
	v_mfma_f32_16x16x32_bf16 v[6:9], v[182:185], v[226:229], v[6:9]
	v_mfma_f32_16x16x32_bf16 v[2:5], v[190:193], v[226:229], v[2:5]
	v_mfma_f32_16x16x32_bf16 v[2:5], v[194:197], v[230:233], v[2:5]
	v_mfma_f32_16x16x32_bf16 v[18:21], v[194:197], v[222:225], v[18:21]
	v_mfma_f32_16x16x32_bf16 v[18:21], v[190:193], v[218:221], v[18:21]
	v_mfma_f32_16x16x32_bf16 v[34:37], v[190:193], v[206:209], v[34:37]
	v_mfma_f32_16x16x32_bf16 v[34:37], v[194:197], v[214:217], v[34:37]
	v_mfma_f32_16x16x32_bf16 v[50:53], v[194:197], v[202:205], v[50:53]
	v_mfma_f32_16x16x32_bf16 v[50:53], v[190:193], v[198:201], v[50:53]
	s_barrier
	s_add_i32 s54, s54, 2
	s_add_u32 s22, s22, 0x100
	s_addc_u32 s23, s23, 0
	s_cmp_gt_u32 s54, 61
	s_cbranch_scc0 .LBB0_612
	s_and_b64 vcc, exec, s[16:17]
	s_cbranch_vccz .LBB0_615
	s_barrier

.LBB0_844:
	s_add_i32 s35, s52, 0xfffe8000
	s_and_b32 s34, s30, 0x100
	s_and_b32 s35, s35, 0x3e0000
	s_or_b32 s34, s34, s35
	s_add_u32 s53, s28, s34
	s_addc_u32 s55, s29, 0
	s_add_u32 s34, s30, 0x100
	s_addc_u32 s35, s31, 0
	s_add_i32 s37, s52, 0xffff8000
	s_and_b32 s36, s34, 0x100
	s_and_b32 s37, s37, 0x7e0000
	s_or_b32 s36, s37, s36
	s_add_u32 s36, s28, s36
	s_addc_u32 s37, s29, 0
	s_add_u32 s54, s49, s30
	s_addc_u32 s31, s50, s31
	s_add_i32 s38, s30, 0x180
	s_and_b32 s38, s38, 0x180
	s_and_b32 s39, s52, 0x7e0000
	s_or_b32 s38, s39, s38
	s_add_u32 s56, s28, s38
	s_addc_u32 s57, s29, 0
	s_cmpk_eq_i32 s30, 0x3f00
	s_cselect_b32 s39, s1, s37
	s_cselect_b32 s38, s21, s36
	s_cselect_b32 s37, s23, s31
	s_cselect_b32 s36, s22, s54
	s_cselect_b32 s31, s48, s57
	s_cselect_b32 s30, s27, s56
	s_add_i32 s56, 0, 0x10000
	v_add_u32_e32 v124, s56, v211
	ds_read_b128 v[104:107], v124
	ds_read_b128 v[108:111], v124 offset:1024
	ds_read_b128 v[120:123], v124 offset:2048
	ds_read_b128 v[124:127], v124 offset:3072
	ds_read_b128 v[144:147], v214
	ds_read_b128 v[148:151], v214 offset:1024
	ds_read_b128 v[152:155], v214 offset:2048
	ds_read_b128 v[156:159], v214 offset:3072
	s_add_u32 s54, s53, 0x10080
	s_addc_u32 s55, s55, 0
	s_add_i32 m0, s3, 0xc000
	ds_read_b128 v[160:163], v215
	ds_read_b128 v[164:167], v215 offset:1024
	ds_read_b128 v[168:171], v215 offset:2048
	ds_read_b128 v[172:175], v215 offset:3072
	ds_read_b128 v[176:179], v215 offset:4096
	ds_read_b128 v[180:183], v215 offset:5120
	ds_read_b128 v[192:195], v215 offset:6144
	ds_read_b128 v[196:199], v215 offset:7168
	global_load_lds_dwordx4 v184, s[54:55]
	s_add_i32 m0, s3, 0xe000
	s_nop 0
	global_load_lds_dwordx4 v188, s[54:55]
	s_waitcnt vmcnt(8)
	s_waitcnt lgkmcnt(0)
	s_barrier
	s_waitcnt lgkmcnt(0)
	v_mfma_f32_16x16x32_bf16 v[140:143], v[104:107], v[160:163], v[140:143]
	v_mfma_f32_16x16x32_bf16 v[140:143], v[108:111], v[164:167], v[140:143]
	v_mfma_f32_16x16x32_bf16 v[116:119], v[108:111], v[172:175], v[116:119]
	v_mfma_f32_16x16x32_bf16 v[116:119], v[104:107], v[168:171], v[116:119]
	v_mfma_f32_16x16x32_bf16 v[92:95], v[104:107], v[176:179], v[92:95]
	v_mfma_f32_16x16x32_bf16 v[92:95], v[108:111], v[180:183], v[92:95]
	v_mfma_f32_16x16x32_bf16 v[76:79], v[108:111], v[196:199], v[76:79]
	v_mfma_f32_16x16x32_bf16 v[76:79], v[104:107], v[192:195], v[76:79]
	v_mfma_f32_16x16x32_bf16 v[72:75], v[120:123], v[192:195], v[72:75]
	v_mfma_f32_16x16x32_bf16 v[72:75], v[124:127], v[196:199], v[72:75]
	v_mfma_f32_16x16x32_bf16 v[88:91], v[124:127], v[180:183], v[88:91]
	v_mfma_f32_16x16x32_bf16 v[88:91], v[120:123], v[176:179], v[88:91]
	v_mfma_f32_16x16x32_bf16 v[112:115], v[120:123], v[168:171], v[112:115]
	v_mfma_f32_16x16x32_bf16 v[112:115], v[124:127], v[172:175], v[112:115]
	v_mfma_f32_16x16x32_bf16 v[136:139], v[124:127], v[164:167], v[136:139]
	v_mfma_f32_16x16x32_bf16 v[136:139], v[120:123], v[160:163], v[136:139]
	v_mfma_f32_16x16x32_bf16 v[132:135], v[144:147], v[160:163], v[132:135]
	v_mfma_f32_16x16x32_bf16 v[132:135], v[148:151], v[164:167], v[132:135]
	v_mfma_f32_16x16x32_bf16 v[100:103], v[148:151], v[172:175], v[100:103]
	v_mfma_f32_16x16x32_bf16 v[100:103], v[144:147], v[168:171], v[100:103]
	v_mfma_f32_16x16x32_bf16 v[84:87], v[144:147], v[176:179], v[84:87]
	v_mfma_f32_16x16x32_bf16 v[84:87], v[148:151], v[180:183], v[84:87]
	v_mfma_f32_16x16x32_bf16 v[68:71], v[148:151], v[196:199], v[68:71]
	v_mfma_f32_16x16x32_bf16 v[68:71], v[144:147], v[192:195], v[68:71]
	v_mfma_f32_16x16x32_bf16 v[64:67], v[152:155], v[192:195], v[64:67]
	v_mfma_f32_16x16x32_bf16 v[64:67], v[156:159], v[196:199], v[64:67]
	v_mfma_f32_16x16x32_bf16 v[80:83], v[156:159], v[180:183], v[80:83]
	v_mfma_f32_16x16x32_bf16 v[80:83], v[152:155], v[176:179], v[80:83]
	v_mfma_f32_16x16x32_bf16 v[96:99], v[152:155], v[168:171], v[96:99]
	v_mfma_f32_16x16x32_bf16 v[96:99], v[156:159], v[172:175], v[96:99]
	v_mfma_f32_16x16x32_bf16 v[128:131], v[156:159], v[164:167], v[128:131]
	v_mfma_f32_16x16x32_bf16 v[128:131], v[152:155], v[160:163], v[128:131]
	s_barrier
	s_add_i32 s53, s56, s2
	v_lshl_add_u64 v[200:201], s[36:37], 0, v[186:187]
	s_mov_b32 m0, s53
	ds_read_b128 v[160:163], v215 offset:16384
	ds_read_b128 v[164:167], v215 offset:17408
	ds_read_b128 v[168:171], v215 offset:18432
	ds_read_b128 v[172:175], v215 offset:19456
	ds_read_b128 v[176:179], v215 offset:20480
	ds_read_b128 v[180:183], v215 offset:21504
	ds_read_b128 v[192:195], v215 offset:22528
	ds_read_b128 v[196:199], v215 offset:23552
	global_load_lds_dwordx4 v[200:201], off
	s_add_i32 m0, s53, 0x2000
	s_add_u32 s54, s36, 0x208000
	v_lshl_add_u64 v[202:203], s[36:37], 0, v[190:191]
	s_addc_u32 s55, s37, 0
	s_add_i32 s53, s45, s2
	global_load_lds_dwordx4 v[202:203], off
	s_mov_b32 m0, s53
	s_nop 0
	global_load_lds_dwordx4 v186, s[54:55]
	s_add_i32 m0, s53, 0x2000
	s_nop 0
	global_load_lds_dwordx4 v190, s[54:55]
	s_mov_b32 m0, s3
	s_nop 0
	global_load_lds_dwordx4 v184, s[38:39]
	s_mov_b32 m0, s33
	s_nop 0
	global_load_lds_dwordx4 v188, s[38:39]
	s_waitcnt vmcnt(8)
	s_waitcnt lgkmcnt(0)
	s_barrier
	s_waitcnt lgkmcnt(0)
	v_mfma_f32_16x16x32_bf16 v[60:63], v[104:107], v[160:163], v[60:63]
	v_mfma_f32_16x16x32_bf16 v[60:63], v[108:111], v[164:167], v[60:63]
	v_mfma_f32_16x16x32_bf16 v[44:47], v[108:111], v[172:175], v[44:47]
	v_mfma_f32_16x16x32_bf16 v[44:47], v[104:107], v[168:171], v[44:47]
	v_mfma_f32_16x16x32_bf16 v[28:31], v[104:107], v[176:179], v[28:31]
	v_mfma_f32_16x16x32_bf16 v[28:31], v[108:111], v[180:183], v[28:31]
	v_mfma_f32_16x16x32_bf16 v[12:15], v[108:111], v[196:199], v[12:15]
	v_mfma_f32_16x16x32_bf16 v[12:15], v[104:107], v[192:195], v[12:15]
	v_mfma_f32_16x16x32_bf16 v[8:11], v[120:123], v[192:195], v[8:11]
	v_mfma_f32_16x16x32_bf16 v[8:11], v[124:127], v[196:199], v[8:11]
	v_mfma_f32_16x16x32_bf16 v[24:27], v[124:127], v[180:183], v[24:27]
	v_mfma_f32_16x16x32_bf16 v[24:27], v[120:123], v[176:179], v[24:27]
	v_mfma_f32_16x16x32_bf16 v[40:43], v[120:123], v[168:171], v[40:43]
	v_mfma_f32_16x16x32_bf16 v[40:43], v[124:127], v[172:175], v[40:43]
	v_mfma_f32_16x16x32_bf16 v[56:59], v[124:127], v[164:167], v[56:59]
	v_mfma_f32_16x16x32_bf16 v[56:59], v[120:123], v[160:163], v[56:59]
	v_mfma_f32_16x16x32_bf16 v[52:55], v[144:147], v[160:163], v[52:55]
	v_mfma_f32_16x16x32_bf16 v[52:55], v[148:151], v[164:167], v[52:55]
	v_mfma_f32_16x16x32_bf16 v[36:39], v[148:151], v[172:175], v[36:39]
	v_mfma_f32_16x16x32_bf16 v[36:39], v[144:147], v[168:171], v[36:39]
	v_mfma_f32_16x16x32_bf16 v[20:23], v[144:147], v[176:179], v[20:23]
	v_mfma_f32_16x16x32_bf16 v[20:23], v[148:151], v[180:183], v[20:23]
	v_mfma_f32_16x16x32_bf16 v[4:7], v[148:151], v[196:199], v[4:7]
	v_mfma_f32_16x16x32_bf16 v[4:7], v[144:147], v[192:195], v[4:7]
	v_mfma_f32_16x16x32_bf16 v[0:3], v[152:155], v[192:195], v[0:3]
	v_mfma_f32_16x16x32_bf16 v[0:3], v[156:159], v[196:199], v[0:3]
	v_mfma_f32_16x16x32_bf16 v[16:19], v[156:159], v[180:183], v[16:19]
	v_mfma_f32_16x16x32_bf16 v[16:19], v[152:155], v[176:179], v[16:19]
	v_mfma_f32_16x16x32_bf16 v[32:35], v[152:155], v[168:171], v[32:35]
	v_mfma_f32_16x16x32_bf16 v[32:35], v[156:159], v[172:175], v[32:35]
	v_mfma_f32_16x16x32_bf16 v[48:51], v[156:159], v[164:167], v[48:51]
	v_mfma_f32_16x16x32_bf16 v[48:51], v[152:155], v[160:163], v[48:51]
	s_barrier
	s_add_i32 s53, 0, 0x18000
	s_add_i32 s54, 0, 0x1c000
	v_add_u32_e32 v124, s53, v211
	v_add_u32_e32 v156, s54, v211
	ds_read_b128 v[104:107], v124
	ds_read_b128 v[108:111], v124 offset:1024
	ds_read_b128 v[120:123], v124 offset:2048
	ds_read_b128 v[124:127], v124 offset:3072
	ds_read_b128 v[144:147], v156
	ds_read_b128 v[148:151], v156 offset:1024
	ds_read_b128 v[152:155], v156 offset:2048
	ds_read_b128 v[156:159], v156 offset:3072
	s_add_u32 s38, s38, 0x10000
	s_addc_u32 s39, s39, 0
	s_mov_b32 m0, s40
	ds_read_b128 v[160:163], v215 offset:32768
	ds_read_b128 v[164:167], v215 offset:33792
	ds_read_b128 v[168:171], v215 offset:34816
	ds_read_b128 v[172:175], v215 offset:35840
	ds_read_b128 v[176:179], v215 offset:36864
	ds_read_b128 v[180:183], v215 offset:37888
	ds_read_b128 v[192:195], v215 offset:38912
	ds_read_b128 v[196:199], v215 offset:39936
	global_load_lds_dwordx4 v184, s[38:39]
	v_lshl_add_u64 v[204:205], s[38:39], 0, v[188:189]
	s_mov_b32 m0, s41
	s_nop 0
	global_load_lds_dwordx4 v[204:205], off
	s_waitcnt vmcnt(8)
	s_waitcnt lgkmcnt(0)
	s_barrier
	s_waitcnt lgkmcnt(0)
	v_mfma_f32_16x16x32_bf16 v[140:143], v[104:107], v[160:163], v[140:143]
	v_mfma_f32_16x16x32_bf16 v[140:143], v[108:111], v[164:167], v[140:143]
	v_mfma_f32_16x16x32_bf16 v[116:119], v[108:111], v[172:175], v[116:119]
	v_mfma_f32_16x16x32_bf16 v[116:119], v[104:107], v[168:171], v[116:119]
	v_mfma_f32_16x16x32_bf16 v[92:95], v[104:107], v[176:179], v[92:95]
	v_mfma_f32_16x16x32_bf16 v[92:95], v[108:111], v[180:183], v[92:95]
	v_mfma_f32_16x16x32_bf16 v[76:79], v[108:111], v[196:199], v[76:79]
	v_mfma_f32_16x16x32_bf16 v[76:79], v[104:107], v[192:195], v[76:79]
	v_mfma_f32_16x16x32_bf16 v[72:75], v[120:123], v[192:195], v[72:75]
	v_mfma_f32_16x16x32_bf16 v[72:75], v[124:127], v[196:199], v[72:75]
	v_mfma_f32_16x16x32_bf16 v[88:91], v[124:127], v[180:183], v[88:91]
	v_mfma_f32_16x16x32_bf16 v[88:91], v[120:123], v[176:179], v[88:91]
	v_mfma_f32_16x16x32_bf16 v[112:115], v[120:123], v[168:171], v[112:115]
	v_mfma_f32_16x16x32_bf16 v[112:115], v[124:127], v[172:175], v[112:115]
	v_mfma_f32_16x16x32_bf16 v[136:139], v[124:127], v[164:167], v[136:139]
	v_mfma_f32_16x16x32_bf16 v[136:139], v[120:123], v[160:163], v[136:139]
	v_mfma_f32_16x16x32_bf16 v[132:135], v[144:147], v[160:163], v[132:135]
	v_mfma_f32_16x16x32_bf16 v[132:135], v[148:151], v[164:167], v[132:135]
	v_mfma_f32_16x16x32_bf16 v[100:103], v[148:151], v[172:175], v[100:103]
	v_mfma_f32_16x16x32_bf16 v[100:103], v[144:147], v[168:171], v[100:103]
	v_mfma_f32_16x16x32_bf16 v[84:87], v[144:147], v[176:179], v[84:87]
	v_mfma_f32_16x16x32_bf16 v[84:87], v[148:151], v[180:183], v[84:87]
	v_mfma_f32_16x16x32_bf16 v[68:71], v[148:151], v[196:199], v[68:71]
	v_mfma_f32_16x16x32_bf16 v[68:71], v[144:147], v[192:195], v[68:71]
	v_mfma_f32_16x16x32_bf16 v[64:67], v[152:155], v[192:195], v[64:67]
	v_mfma_f32_16x16x32_bf16 v[64:67], v[156:159], v[196:199], v[64:67]
	v_mfma_f32_16x16x32_bf16 v[80:83], v[156:159], v[180:183], v[80:83]
	v_mfma_f32_16x16x32_bf16 v[80:83], v[152:155], v[176:179], v[80:83]
	v_mfma_f32_16x16x32_bf16 v[96:99], v[152:155], v[168:171], v[96:99]
	v_mfma_f32_16x16x32_bf16 v[96:99], v[156:159], v[172:175], v[96:99]
	v_mfma_f32_16x16x32_bf16 v[128:131], v[156:159], v[164:167], v[128:131]
	v_mfma_f32_16x16x32_bf16 v[128:131], v[152:155], v[160:163], v[128:131]
	s_barrier
	s_add_i32 s38, s53, s2
	v_lshl_add_u64 v[200:201], v[200:201], 0, s[16:17]
	s_mov_b32 m0, s38
	ds_read_b128 v[160:163], v215 offset:49152
	ds_read_b128 v[164:167], v215 offset:50176
	ds_read_b128 v[168:171], v215 offset:51200
	ds_read_b128 v[172:175], v215 offset:52224
	ds_read_b128 v[176:179], v215 offset:53248
	ds_read_b128 v[180:183], v215 offset:54272
	ds_read_b128 v[192:195], v215 offset:55296
	ds_read_b128 v[196:199], v215 offset:56320
	global_load_lds_dwordx4 v[200:201], off
	s_add_i32 m0, s38, 0x2000
	s_add_u32 s36, s36, 0x208080
	v_lshl_add_u64 v[200:201], v[202:203], 0, s[16:17]
	s_addc_u32 s37, s37, 0
	s_add_i32 s38, s54, s2
	global_load_lds_dwordx4 v[200:201], off
	s_mov_b32 m0, s38
	s_nop 0
	global_load_lds_dwordx4 v186, s[36:37]
	s_add_i32 m0, s38, 0x2000
	s_nop 0
	global_load_lds_dwordx4 v190, s[36:37]
	s_mov_b32 m0, s43
	s_nop 0
	global_load_lds_dwordx4 v184, s[30:31]
	v_lshl_add_u64 v[200:201], s[30:31], 0, v[188:189]
	s_mov_b32 m0, s44
	s_nop 0
	global_load_lds_dwordx4 v[200:201], off
	s_waitcnt vmcnt(8)
	s_waitcnt lgkmcnt(0)
	s_barrier
	s_waitcnt lgkmcnt(0)
	v_mfma_f32_16x16x32_bf16 v[60:63], v[104:107], v[160:163], v[60:63]
	v_mfma_f32_16x16x32_bf16 v[60:63], v[108:111], v[164:167], v[60:63]
	v_mfma_f32_16x16x32_bf16 v[44:47], v[108:111], v[172:175], v[44:47]
	v_mfma_f32_16x16x32_bf16 v[44:47], v[104:107], v[168:171], v[44:47]
	v_mfma_f32_16x16x32_bf16 v[28:31], v[104:107], v[176:179], v[28:31]
	v_mfma_f32_16x16x32_bf16 v[28:31], v[108:111], v[180:183], v[28:31]
	v_mfma_f32_16x16x32_bf16 v[12:15], v[108:111], v[196:199], v[12:15]
	v_mfma_f32_16x16x32_bf16 v[12:15], v[104:107], v[192:195], v[12:15]
	v_mfma_f32_16x16x32_bf16 v[8:11], v[120:123], v[192:195], v[8:11]
	v_mfma_f32_16x16x32_bf16 v[8:11], v[124:127], v[196:199], v[8:11]
	v_mfma_f32_16x16x32_bf16 v[24:27], v[124:127], v[180:183], v[24:27]
	v_mfma_f32_16x16x32_bf16 v[24:27], v[120:123], v[176:179], v[24:27]
	v_mfma_f32_16x16x32_bf16 v[40:43], v[120:123], v[168:171], v[40:43]
	v_mfma_f32_16x16x32_bf16 v[40:43], v[124:127], v[172:175], v[40:43]
	v_mfma_f32_16x16x32_bf16 v[56:59], v[124:127], v[164:167], v[56:59]
	v_mfma_f32_16x16x32_bf16 v[56:59], v[120:123], v[160:163], v[56:59]
	v_mfma_f32_16x16x32_bf16 v[52:55], v[144:147], v[160:163], v[52:55]
	v_mfma_f32_16x16x32_bf16 v[52:55], v[148:151], v[164:167], v[52:55]
	v_mfma_f32_16x16x32_bf16 v[36:39], v[148:151], v[172:175], v[36:39]
	v_mfma_f32_16x16x32_bf16 v[36:39], v[144:147], v[168:171], v[36:39]
	v_mfma_f32_16x16x32_bf16 v[20:23], v[144:147], v[176:179], v[20:23]
	v_mfma_f32_16x16x32_bf16 v[20:23], v[148:151], v[180:183], v[20:23]
	v_mfma_f32_16x16x32_bf16 v[4:7], v[148:151], v[196:199], v[4:7]
	v_mfma_f32_16x16x32_bf16 v[4:7], v[144:147], v[192:195], v[4:7]
	v_mfma_f32_16x16x32_bf16 v[0:3], v[152:155], v[192:195], v[0:3]
	v_mfma_f32_16x16x32_bf16 v[0:3], v[156:159], v[196:199], v[0:3]
	v_mfma_f32_16x16x32_bf16 v[16:19], v[156:159], v[180:183], v[16:19]
	v_mfma_f32_16x16x32_bf16 v[16:19], v[152:155], v[176:179], v[16:19]
	v_mfma_f32_16x16x32_bf16 v[32:35], v[152:155], v[168:171], v[32:35]
	v_mfma_f32_16x16x32_bf16 v[32:35], v[156:159], v[172:175], v[32:35]
	v_mfma_f32_16x16x32_bf16 v[48:51], v[156:159], v[164:167], v[48:51]
	v_mfma_f32_16x16x32_bf16 v[48:51], v[152:155], v[160:163], v[48:51]
	s_barrier
	s_add_i32 s51, s51, 2
	s_add_i32 s52, s52, 0x10000
	s_cmpk_gt_u32 s51, 0x7d
	s_mov_b64 s[30:31], s[34:35]
	s_cbranch_scc0 .LBB0_844
	s_and_b64 vcc, exec, s[18:19]
	s_cbranch_vccz .LBB0_847
	s_barrier
